# QK+PV LDS fragment prefetch (K 7-deep, V 5-6 deep), deferred row-sum adds and running max in MFMA shadows; down-proj epilogue residual loads issued together with counted vmcnt
# speedup vs baseline: 1.0062x; 1.0062x over previous
.LBB0_300:
	s_add_i32 s6, s14, -4
	s_and_b32 s6, s6, 2
	s_mul_i32 s7, s6, 0x3400
	v_add3_u32 v0, v198, s7, v199
	s_addk_i32 s7, 0x3400
	v_add3_u32 v225, v198, s7, v199
	s_mul_i32 s7, s6, 0x2400
	ds_read_b128 v[226:229], v0
	ds_read_b128 v[230:233], v0 offset:32
	ds_read_b128 v[234:237], v0 offset:64
	ds_read_b128 v[238:241], v0 offset:96
	ds_read_b128 v[242:245], v0 offset:128
	ds_read_b128 v[162:165], v0 offset:160
	ds_read_b128 v[166:169], v0 offset:6656
	v_add_f32_e32 v201, v74, v201
	v_add_f32_e32 v247, v75, v76
	v_add_f32_e32 v201, v77, v201
	v_add_f32_e32 v247, v78, v247
	v_add_f32_e32 v201, v79, v201
	v_add_f32_e32 v247, v80, v247
	v_add_f32_e32 v201, v81, v201
	v_add_f32_e32 v247, v82, v247
	v_add_f32_e32 v201, v83, v201
	v_add_f32_e32 v247, v84, v247
	v_add_f32_e32 v201, v85, v201
	v_add_f32_e32 v247, v86, v247
	v_add_f32_e32 v201, v87, v201
	v_add_f32_e32 v247, v88, v247
	s_waitcnt lgkmcnt(6)
	v_mfma_f32_32x32x16_bf16 v[50:65], v[226:229], v[114:117], v[34:49]
	ds_read_b128 v[226:229], v0 offset:6688
	v_add_f32_e32 v201, v89, v201
	v_add_f32_e32 v247, v90, v247
	v_add_f32_e32 v201, v91, v201
	v_add_f32_e32 v247, v92, v247
	v_add_f32_e32 v201, v93, v201
	s_waitcnt lgkmcnt(6)
	v_mfma_f32_32x32x16_bf16 v[50:65], v[230:233], v[118:121], v[50:65]
	ds_read_b128 v[230:233], v0 offset:6720
	v_add_f32_e32 v247, v94, v247
	v_add_f32_e32 v201, v95, v201
	v_add_f32_e32 v247, v96, v247
	v_add_f32_e32 v201, v97, v201
	v_add_f32_e32 v247, v98, v247
	s_waitcnt lgkmcnt(6)
	v_mfma_f32_32x32x16_bf16 v[50:65], v[234:237], v[122:125], v[50:65]
	ds_read_b128 v[234:237], v0 offset:6752
	v_add_f32_e32 v201, v99, v201
	v_add_f32_e32 v247, v100, v247
	v_add_f32_e32 v201, v101, v201
	v_add_f32_e32 v247, v102, v247
	s_waitcnt lgkmcnt(6)
	v_mfma_f32_32x32x16_bf16 v[50:65], v[238:241], v[126:129], v[50:65]
	ds_read_b128 v[238:241], v0 offset:6784
	v_add_f32_e32 v201, v103, v201
	v_add_f32_e32 v247, v104, v247
	v_add_f32_e32 v201, v105, v201
	v_add_f32_e32 v247, v106, v247
	s_waitcnt lgkmcnt(6)
	v_mfma_f32_32x32x16_bf16 v[50:65], v[242:245], v[130:133], v[50:65]
	ds_read_b128 v[242:245], v0 offset:6816
	v_add_f32_e32 v201, v107, v201
	v_add_f32_e32 v247, v108, v247
	v_add_f32_e32 v201, v109, v201
	v_add_f32_e32 v247, v110, v247
	s_waitcnt lgkmcnt(6)
	v_mfma_f32_32x32x16_bf16 v[50:65], v[162:165], v[134:137], v[50:65]
	ds_read_b128 v[162:165], v225
	v_add_f32_e32 v201, v111, v201
	v_add_f32_e32 v247, v112, v247
	v_add_f32_e32 v201, v113, v201
	v_add_f32_e32 v247, v246, v247
	s_waitcnt lgkmcnt(6)
	v_mfma_f32_32x32x16_bf16 v[66:81], v[166:169], v[114:117], v[34:49]
	ds_read_b128 v[166:169], v225 offset:32
	v_add_f32_e32 v201, v202, v201
	v_add_f32_e32 v247, v203, v247
	v_add_f32_e32 v201, v204, v201
	v_add_f32_e32 v247, v205, v247
	s_waitcnt lgkmcnt(6)
	v_mfma_f32_32x32x16_bf16 v[66:81], v[226:229], v[118:121], v[66:81]
	ds_read_b128 v[226:229], v225 offset:64
	v_add_f32_e32 v201, v206, v201
	v_add_f32_e32 v247, v207, v247
	v_add_f32_e32 v201, v208, v201
	v_add_f32_e32 v247, v209, v247
	s_waitcnt lgkmcnt(6)
	v_mfma_f32_32x32x16_bf16 v[66:81], v[230:233], v[122:125], v[66:81]
	ds_read_b128 v[230:233], v225 offset:96
	v_add_f32_e32 v201, v210, v201
	v_add_f32_e32 v247, v211, v247
	v_add_f32_e32 v201, v212, v201
	v_add_f32_e32 v247, v213, v247
	v_max3_f32 v0, v50, v51, v52
	v_max3_f32 v0, v0, v53, v54
	s_waitcnt lgkmcnt(6)
	v_mfma_f32_32x32x16_bf16 v[66:81], v[234:237], v[126:129], v[66:81]
	ds_read_b128 v[234:237], v225 offset:128
	v_add_f32_e32 v201, v214, v201
	v_add_f32_e32 v247, v215, v247
	v_add_f32_e32 v201, v216, v201
	v_add_f32_e32 v247, v217, v247
	v_max3_f32 v0, v0, v55, v56
	v_max3_f32 v0, v0, v57, v58
	s_waitcnt lgkmcnt(6)
	v_mfma_f32_32x32x16_bf16 v[66:81], v[238:241], v[130:133], v[66:81]
	ds_read_b128 v[238:241], v225 offset:160
	v_add_f32_e32 v201, v218, v201
	v_add_f32_e32 v247, v219, v247
	v_add_f32_e32 v201, v220, v201
	v_add_f32_e32 v247, v221, v247
	v_max3_f32 v0, v0, v59, v60
	v_max3_f32 v0, v0, v61, v62
	s_waitcnt lgkmcnt(6)
	v_mfma_f32_32x32x16_bf16 v[66:81], v[242:245], v[134:137], v[66:81]
	ds_read_b128 v[242:245], v225 offset:6656
	v_add_f32_e32 v201, v222, v201
	v_add_f32_e32 v247, v223, v247
	v_add_f32_e32 v201, v224, v201
	v_add_f32_e32 v201, v247, v201
	v_max3_f32 v0, v0, v63, v64
	v_max3_f32 v0, v0, v65, v65
	s_waitcnt lgkmcnt(6)
	v_mfma_f32_32x32x16_bf16 v[82:97], v[162:165], v[114:117], v[34:49]
	ds_read_b128 v[162:165], v225 offset:6688
	s_waitcnt lgkmcnt(6)
	v_mfma_f32_32x32x16_bf16 v[82:97], v[166:169], v[118:121], v[82:97]
	ds_read_b128 v[166:169], v225 offset:6720
	v_add3_u32 v247, v198, s7, v200
	s_waitcnt lgkmcnt(6)
	v_mfma_f32_32x32x16_bf16 v[82:97], v[226:229], v[122:125], v[82:97]
	ds_read_b128 v[226:229], v225 offset:6752
	v_max3_f32 v0, v0, v66, v67
	v_max3_f32 v0, v0, v68, v69
	s_waitcnt lgkmcnt(6)
	v_mfma_f32_32x32x16_bf16 v[82:97], v[230:233], v[126:129], v[82:97]
	ds_read_b128 v[230:233], v225 offset:6784
	v_max3_f32 v0, v0, v70, v71
	v_max3_f32 v0, v0, v72, v73
	s_waitcnt lgkmcnt(6)
	v_mfma_f32_32x32x16_bf16 v[82:97], v[234:237], v[130:133], v[82:97]
	ds_read_b128 v[234:237], v225 offset:6816
	v_max3_f32 v0, v0, v74, v75
	v_max3_f32 v0, v0, v76, v77
	s_waitcnt lgkmcnt(6)
	v_mfma_f32_32x32x16_bf16 v[82:97], v[238:241], v[134:137], v[82:97]
	ds_read_b128 v[238:241], v247 offset:53248
	v_max3_f32 v0, v0, v78, v79
	v_max3_f32 v0, v0, v80, v81
	s_waitcnt lgkmcnt(6)
	v_mfma_f32_32x32x16_bf16 v[98:113], v[242:245], v[114:117], v[34:49]
	ds_read_b128 v[242:245], v247 offset:57856
	s_waitcnt lgkmcnt(6)
	v_mfma_f32_32x32x16_bf16 v[98:113], v[162:165], v[118:121], v[98:113]
	s_waitcnt lgkmcnt(5)
	v_mfma_f32_32x32x16_bf16 v[98:113], v[166:169], v[122:125], v[98:113]
	s_waitcnt lgkmcnt(4)
	v_mfma_f32_32x32x16_bf16 v[98:113], v[226:229], v[126:129], v[98:113]
	ds_read_b128 v[226:229], v247 offset:53280
	s_waitcnt lgkmcnt(4)
	v_mfma_f32_32x32x16_bf16 v[98:113], v[230:233], v[130:133], v[98:113]
	ds_read_b128 v[230:233], v247 offset:57888
	s_waitcnt lgkmcnt(4)
	v_mfma_f32_32x32x16_bf16 v[98:113], v[234:237], v[134:137], v[98:113]
	ds_read_b128 v[234:237], v247 offset:53312
	v_max3_f32 v0, v0, v82, v83
	v_max3_f32 v0, v0, v84, v85
	v_max3_f32 v0, v0, v86, v87
	v_max3_f32 v0, v0, v88, v89
	v_max3_f32 v0, v0, v90, v91
	v_max3_f32 v0, v0, v92, v93
	v_max3_f32 v0, v0, v94, v95
	v_max3_f32 v0, v0, v96, v97
	s_nop 4
	v_max3_f32 v0, v0, v98, v99
	v_max3_f32 v0, v0, v100, v101
	v_max3_f32 v0, v0, v102, v103
	v_max3_f32 v0, v0, v104, v105
	v_max3_f32 v0, v0, v106, v107
	v_max3_f32 v0, v0, v108, v109
	v_max3_f32 v0, v0, v110, v111
	v_max3_f32 v0, v0, v112, v113
	v_mov_b32_e32 v162, v0
	s_nop 1
	v_permlane32_swap_b32_e32 v0, v162
	v_max_f32_e32 v162, v162, v162
	v_max_f32_e32 v0, v0, v0
	v_max_f32_e32 v0, v0, v162
	v_cmp_lt_f32_e32 vcc, s50, v0
	s_cbranch_vccz .LBB0_302
	v_max_f32_e32 v0, v0, v0
	v_max_f32_e32 v0, 0, v0
	v_exp_f32_e64 v162, -v0
	v_pk_add_f32 v[50:51], v[50:51], v[0:1] op_sel_hi:[1,0] neg_lo:[0,1] neg_hi:[0,1]
	v_pk_add_f32 v[66:67], v[66:67], v[0:1] op_sel_hi:[1,0] neg_lo:[0,1] neg_hi:[0,1]
	v_pk_add_f32 v[82:83], v[82:83], v[0:1] op_sel_hi:[1,0] neg_lo:[0,1] neg_hi:[0,1]
	v_mul_f32_e32 v201, v201, v162
	v_pk_mul_f32 v[16:17], v[16:17], v[162:163] op_sel_hi:[1,0]
	v_pk_mul_f32 v[14:15], v[14:15], v[162:163] op_sel_hi:[1,0]
	v_pk_mul_f32 v[12:13], v[12:13], v[162:163] op_sel_hi:[1,0]
	v_pk_mul_f32 v[10:11], v[10:11], v[162:163] op_sel_hi:[1,0]
	v_pk_mul_f32 v[8:9], v[8:9], v[162:163] op_sel_hi:[1,0]
	v_pk_mul_f32 v[6:7], v[6:7], v[162:163] op_sel_hi:[1,0]
	v_pk_mul_f32 v[4:5], v[4:5], v[162:163] op_sel_hi:[1,0]
	v_pk_mul_f32 v[2:3], v[2:3], v[162:163] op_sel_hi:[1,0]
	v_pk_mul_f32 v[32:33], v[32:33], v[162:163] op_sel_hi:[1,0]
	v_pk_mul_f32 v[30:31], v[30:31], v[162:163] op_sel_hi:[1,0]
	v_pk_mul_f32 v[28:29], v[28:29], v[162:163] op_sel_hi:[1,0]
	v_pk_mul_f32 v[26:27], v[26:27], v[162:163] op_sel_hi:[1,0]
	v_pk_mul_f32 v[24:25], v[24:25], v[162:163] op_sel_hi:[1,0]
	v_pk_mul_f32 v[22:23], v[22:23], v[162:163] op_sel_hi:[1,0]
	v_pk_mul_f32 v[20:21], v[20:21], v[162:163] op_sel_hi:[1,0]
	v_pk_mul_f32 v[18:19], v[18:19], v[162:163] op_sel_hi:[1,0]
	v_pk_add_f32 v[98:99], v[98:99], v[0:1] op_sel_hi:[1,0] neg_lo:[0,1] neg_hi:[0,1]
	v_pk_add_f32 v[52:53], v[52:53], v[0:1] op_sel_hi:[1,0] neg_lo:[0,1] neg_hi:[0,1]
	v_pk_add_f32 v[68:69], v[68:69], v[0:1] op_sel_hi:[1,0] neg_lo:[0,1] neg_hi:[0,1]
	v_pk_add_f32 v[84:85], v[84:85], v[0:1] op_sel_hi:[1,0] neg_lo:[0,1] neg_hi:[0,1]
	v_pk_add_f32 v[100:101], v[100:101], v[0:1] op_sel_hi:[1,0] neg_lo:[0,1] neg_hi:[0,1]
	v_pk_add_f32 v[54:55], v[54:55], v[0:1] op_sel_hi:[1,0] neg_lo:[0,1] neg_hi:[0,1]
	v_pk_add_f32 v[70:71], v[70:71], v[0:1] op_sel_hi:[1,0] neg_lo:[0,1] neg_hi:[0,1]
	v_pk_add_f32 v[86:87], v[86:87], v[0:1] op_sel_hi:[1,0] neg_lo:[0,1] neg_hi:[0,1]
	v_pk_add_f32 v[102:103], v[102:103], v[0:1] op_sel_hi:[1,0] neg_lo:[0,1] neg_hi:[0,1]
	v_pk_add_f32 v[56:57], v[56:57], v[0:1] op_sel_hi:[1,0] neg_lo:[0,1] neg_hi:[0,1]
	v_pk_add_f32 v[72:73], v[72:73], v[0:1] op_sel_hi:[1,0] neg_lo:[0,1] neg_hi:[0,1]
	v_pk_add_f32 v[88:89], v[88:89], v[0:1] op_sel_hi:[1,0] neg_lo:[0,1] neg_hi:[0,1]
	v_pk_add_f32 v[104:105], v[104:105], v[0:1] op_sel_hi:[1,0] neg_lo:[0,1] neg_hi:[0,1]
	v_pk_add_f32 v[58:59], v[58:59], v[0:1] op_sel_hi:[1,0] neg_lo:[0,1] neg_hi:[0,1]
	v_pk_add_f32 v[74:75], v[74:75], v[0:1] op_sel_hi:[1,0] neg_lo:[0,1] neg_hi:[0,1]
	v_pk_add_f32 v[90:91], v[90:91], v[0:1] op_sel_hi:[1,0] neg_lo:[0,1] neg_hi:[0,1]
	v_pk_add_f32 v[106:107], v[106:107], v[0:1] op_sel_hi:[1,0] neg_lo:[0,1] neg_hi:[0,1]
	v_pk_add_f32 v[60:61], v[60:61], v[0:1] op_sel_hi:[1,0] neg_lo:[0,1] neg_hi:[0,1]
	v_pk_add_f32 v[76:77], v[76:77], v[0:1] op_sel_hi:[1,0] neg_lo:[0,1] neg_hi:[0,1]
	v_pk_add_f32 v[92:93], v[92:93], v[0:1] op_sel_hi:[1,0] neg_lo:[0,1] neg_hi:[0,1]
	v_pk_add_f32 v[108:109], v[108:109], v[0:1] op_sel_hi:[1,0] neg_lo:[0,1] neg_hi:[0,1]
	v_pk_add_f32 v[62:63], v[62:63], v[0:1] op_sel_hi:[1,0] neg_lo:[0,1] neg_hi:[0,1]
	v_pk_add_f32 v[78:79], v[78:79], v[0:1] op_sel_hi:[1,0] neg_lo:[0,1] neg_hi:[0,1]
	v_pk_add_f32 v[94:95], v[94:95], v[0:1] op_sel_hi:[1,0] neg_lo:[0,1] neg_hi:[0,1]
	v_pk_add_f32 v[110:111], v[110:111], v[0:1] op_sel_hi:[1,0] neg_lo:[0,1] neg_hi:[0,1]
	v_pk_add_f32 v[64:65], v[64:65], v[0:1] op_sel_hi:[1,0] neg_lo:[0,1] neg_hi:[0,1]
	v_pk_add_f32 v[80:81], v[80:81], v[0:1] op_sel_hi:[1,0] neg_lo:[0,1] neg_hi:[0,1]
	v_pk_add_f32 v[96:97], v[96:97], v[0:1] op_sel_hi:[1,0] neg_lo:[0,1] neg_hi:[0,1]
	v_pk_add_f32 v[112:113], v[112:113], v[0:1] op_sel_hi:[1,0] neg_lo:[0,1] neg_hi:[0,1]
	v_sub_f32_e32 v49, v49, v0
	v_sub_f32_e32 v48, v48, v0
	v_sub_f32_e32 v47, v47, v0
	v_sub_f32_e32 v46, v46, v0
	v_sub_f32_e32 v45, v45, v0
	v_sub_f32_e32 v44, v44, v0
	v_sub_f32_e32 v43, v43, v0
	v_sub_f32_e32 v42, v42, v0
	v_sub_f32_e32 v41, v41, v0
	v_sub_f32_e32 v40, v40, v0
	v_sub_f32_e32 v39, v39, v0
	v_sub_f32_e32 v38, v38, v0
	v_sub_f32_e32 v37, v37, v0
	v_sub_f32_e32 v36, v36, v0
	v_sub_f32_e32 v35, v35, v0
	v_sub_f32_e32 v34, v34, v0
.LBB0_302:
	s_addk_i32 s7, 0x2400
	v_add3_u32 v0, v198, s7, v200
	v_exp_f32_e32 v246, v50
	v_exp_f32_e32 v202, v51
	v_exp_f32_e32 v203, v52
	v_exp_f32_e32 v204, v53
	v_exp_f32_e32 v205, v54
	v_exp_f32_e32 v206, v55
	v_exp_f32_e32 v207, v56
	v_exp_f32_e32 v208, v57
	v_cvt_pk_bf16_f32 v166, v246, v202
	v_cvt_pk_bf16_f32 v167, v203, v204
	v_cvt_pk_bf16_f32 v168, v205, v206
	v_cvt_pk_bf16_f32 v169, v207, v208
	v_exp_f32_e32 v209, v58
	v_exp_f32_e32 v210, v59
	s_waitcnt lgkmcnt(4)
	v_mfma_f32_32x32x16_bf16 v[18:33], v[238:241], v[166:169], v[18:33]
	ds_read_b128 v[238:241], v247 offset:57920
	v_exp_f32_e32 v211, v60
	v_exp_f32_e32 v212, v61
	v_exp_f32_e32 v213, v62
	v_exp_f32_e32 v214, v63
	v_exp_f32_e32 v215, v64
	v_exp_f32_e32 v216, v65
	s_waitcnt lgkmcnt(4)
	v_mfma_f32_32x32x16_bf16 v[2:17], v[242:245], v[166:169], v[2:17]
	ds_read_b128 v[242:245], v247 offset:53344
	v_cvt_pk_bf16_f32 v162, v209, v210
	v_cvt_pk_bf16_f32 v163, v211, v212
	v_cvt_pk_bf16_f32 v164, v213, v214
	v_cvt_pk_bf16_f32 v165, v215, v216
	v_exp_f32_e32 v217, v66
	v_exp_f32_e32 v218, v67
	s_waitcnt lgkmcnt(4)
	v_mfma_f32_32x32x16_bf16 v[18:33], v[226:229], v[162:165], v[18:33]
	ds_read_b128 v[226:229], v247 offset:57952
	v_exp_f32_e32 v219, v68
	v_exp_f32_e32 v220, v69
	v_exp_f32_e32 v221, v70
	v_exp_f32_e32 v222, v71
	v_exp_f32_e32 v223, v72
	v_exp_f32_e32 v224, v73
	v_cvt_pk_bf16_f32 v70, v217, v218
	s_waitcnt lgkmcnt(4)
	v_mfma_f32_32x32x16_bf16 v[2:17], v[230:233], v[162:165], v[2:17]
	ds_read_b128 v[230:233], v0 offset:53248
	v_cvt_pk_bf16_f32 v71, v219, v220
	v_cvt_pk_bf16_f32 v72, v221, v222
	v_cvt_pk_bf16_f32 v73, v223, v224
	v_exp_f32_e32 v74, v74
	v_exp_f32_e32 v75, v75
	v_exp_f32_e32 v76, v76
	s_waitcnt lgkmcnt(4)
	v_mfma_f32_32x32x16_bf16 v[18:33], v[234:237], v[70:73], v[18:33]
	ds_read_b128 v[234:237], v0 offset:57856
	v_exp_f32_e32 v77, v77
	v_exp_f32_e32 v78, v78
	v_exp_f32_e32 v79, v79
	v_exp_f32_e32 v80, v80
	v_exp_f32_e32 v81, v81
	v_cvt_pk_bf16_f32 v66, v74, v75
	s_waitcnt lgkmcnt(4)
	v_mfma_f32_32x32x16_bf16 v[2:17], v[238:241], v[70:73], v[2:17]
	ds_read_b128 v[238:241], v0 offset:53280
	v_cvt_pk_bf16_f32 v67, v76, v77
	v_cvt_pk_bf16_f32 v68, v78, v79
	v_cvt_pk_bf16_f32 v69, v80, v81
	v_exp_f32_e32 v82, v82
	v_exp_f32_e32 v83, v83
	s_waitcnt lgkmcnt(4)
	v_mfma_f32_32x32x16_bf16 v[18:33], v[242:245], v[66:69], v[18:33]
	ds_read_b128 v[242:245], v0 offset:57888
	v_exp_f32_e32 v84, v84
	v_exp_f32_e32 v85, v85
	v_exp_f32_e32 v86, v86
	v_exp_f32_e32 v87, v87
	v_exp_f32_e32 v88, v88
	v_exp_f32_e32 v89, v89
	s_waitcnt lgkmcnt(4)
	v_mfma_f32_32x32x16_bf16 v[2:17], v[226:229], v[66:69], v[2:17]
	ds_read_b128 v[226:229], v0 offset:53312
	v_cvt_pk_bf16_f32 v62, v82, v83
	v_cvt_pk_bf16_f32 v63, v84, v85
	v_cvt_pk_bf16_f32 v64, v86, v87
	v_cvt_pk_bf16_f32 v65, v88, v89
	v_exp_f32_e32 v90, v90
	v_exp_f32_e32 v91, v91
	s_waitcnt lgkmcnt(4)
	v_mfma_f32_32x32x16_bf16 v[18:33], v[230:233], v[62:65], v[18:33]
	ds_read_b128 v[230:233], v0 offset:57920
	v_exp_f32_e32 v92, v92
	v_exp_f32_e32 v93, v93
	v_exp_f32_e32 v94, v94
	v_exp_f32_e32 v95, v95
	v_exp_f32_e32 v96, v96
	v_exp_f32_e32 v97, v97
	s_waitcnt lgkmcnt(4)
	v_mfma_f32_32x32x16_bf16 v[2:17], v[234:237], v[62:65], v[2:17]
	ds_read_b128 v[234:237], v0 offset:53344
	v_cvt_pk_bf16_f32 v58, v90, v91
	v_cvt_pk_bf16_f32 v59, v92, v93
	v_cvt_pk_bf16_f32 v60, v94, v95
	v_cvt_pk_bf16_f32 v61, v96, v97
	v_exp_f32_e32 v98, v98
	v_exp_f32_e32 v99, v99
	s_waitcnt lgkmcnt(4)
	v_mfma_f32_32x32x16_bf16 v[18:33], v[238:241], v[58:61], v[18:33]
	ds_read_b128 v[238:241], v0 offset:57952
	v_exp_f32_e32 v100, v100
	v_exp_f32_e32 v101, v101
	v_exp_f32_e32 v102, v102
	v_exp_f32_e32 v103, v103
	v_exp_f32_e32 v104, v104
	v_exp_f32_e32 v105, v105
	v_cvt_pk_bf16_f32 v54, v98, v99
	s_waitcnt lgkmcnt(4)
	v_mfma_f32_32x32x16_bf16 v[2:17], v[242:245], v[58:61], v[2:17]
	v_cvt_pk_bf16_f32 v55, v100, v101
	v_cvt_pk_bf16_f32 v56, v102, v103
	v_cvt_pk_bf16_f32 v57, v104, v105
	v_exp_f32_e32 v106, v106
	v_exp_f32_e32 v107, v107
	v_exp_f32_e32 v108, v108
	s_waitcnt lgkmcnt(3)
	v_mfma_f32_32x32x16_bf16 v[18:33], v[226:229], v[54:57], v[18:33]
	v_exp_f32_e32 v109, v109
	v_exp_f32_e32 v110, v110
	v_exp_f32_e32 v111, v111
	v_exp_f32_e32 v112, v112
	v_exp_f32_e32 v113, v113
	v_cvt_pk_bf16_f32 v50, v106, v107
	s_waitcnt lgkmcnt(2)
	v_mfma_f32_32x32x16_bf16 v[2:17], v[230:233], v[54:57], v[2:17]
	v_cvt_pk_bf16_f32 v51, v108, v109
	v_cvt_pk_bf16_f32 v52, v110, v111
	v_cvt_pk_bf16_f32 v53, v112, v113
	s_add_i32 s15, s14, -2
	s_cmp_ge_u32 s15, s23
	s_waitcnt lgkmcnt(1)
	v_mfma_f32_32x32x16_bf16 v[18:33], v[234:237], v[50:53], v[18:33]
	s_waitcnt lgkmcnt(0)
	v_mfma_f32_32x32x16_bf16 v[2:17], v[238:241], v[50:53], v[2:17]
	s_cbranch_scc1 .LBB0_312
	s_xor_b32 s16, s6, 2
	s_mul_i32 s6, s16, 0x3400
	s_add_i32 s17, s6, 0
	v_add3_u32 v50, s17, v173, v192
	s_and_saveexec_b64 s[6:7], s[0:1]
	s_cbranch_execz .LBB0_305
	s_waitcnt vmcnt(2)
	ds_write_b128 v50, v[138:141]

.LBB0_348:
	s_add_i32 s4, s12, -4
	s_and_b32 s4, s4, 2
	s_mul_i32 s5, s4, 0x2400
	v_add_u32_e32 v0, s5, v163
	ds_read_b128 v[214:217], v0 offset:9216
	ds_read_b128 v[218:221], v0 offset:9248
	ds_read_b128 v[222:225], v0 offset:9280
	ds_read_b128 v[226:229], v0 offset:9312
	ds_read_b128 v[230:233], v0 offset:4608
	ds_read_b128 v[234:237], v0 offset:4640
	ds_read_b128 v[238:241], v0 offset:4672
	v_add_f32_e32 v165, v62, v165
	v_add_f32_e32 v242, v63, v64
	v_add_f32_e32 v165, v65, v165
	v_add_f32_e32 v242, v74, v242
	v_add_f32_e32 v165, v75, v165
	v_add_f32_e32 v242, v76, v242
	v_add_f32_e32 v165, v77, v165
	v_add_f32_e32 v242, v78, v242
	v_add_f32_e32 v165, v79, v165
	v_add_f32_e32 v242, v80, v242
	v_add_f32_e32 v165, v81, v165
	v_add_f32_e32 v242, v106, v242
	s_waitcnt lgkmcnt(6)
	v_mfma_f32_32x32x16_bf16 v[50:65], v[214:217], v[114:117], v[34:49]
	ds_read_b128 v[214:217], v0 offset:4704
	v_add_f32_e32 v165, v107, v165
	v_add_f32_e32 v242, v108, v242
	v_add_f32_e32 v165, v109, v165
	v_add_f32_e32 v242, v110, v242
	v_add_f32_e32 v165, v111, v165
	s_waitcnt lgkmcnt(6)
	v_mfma_f32_32x32x16_bf16 v[50:65], v[218:221], v[118:121], v[50:65]
	ds_read_b128 v[218:221], v0
	v_add_f32_e32 v242, v112, v242
	v_add_f32_e32 v165, v113, v165
	v_add_f32_e32 v242, v82, v242
	v_add_f32_e32 v165, v83, v165
	v_add_f32_e32 v242, v84, v242
	s_waitcnt lgkmcnt(6)
	v_mfma_f32_32x32x16_bf16 v[50:65], v[222:225], v[122:125], v[50:65]
	ds_read_b128 v[222:225], v0 offset:32
	v_add_f32_e32 v165, v85, v165
	v_add_f32_e32 v242, v86, v242
	v_add_f32_e32 v165, v87, v165
	v_add_f32_e32 v242, v88, v242
	v_add_f32_e32 v165, v89, v165
	s_waitcnt lgkmcnt(6)
	v_mfma_f32_32x32x16_bf16 v[50:65], v[226:229], v[126:129], v[50:65]
	ds_read_b128 v[226:229], v0 offset:64
	v_add_f32_e32 v242, v90, v242
	v_add_f32_e32 v165, v91, v165
	v_add_f32_e32 v242, v92, v242
	v_add_f32_e32 v165, v93, v165
	v_add_f32_e32 v242, v94, v242
	s_waitcnt lgkmcnt(6)
	v_mfma_f32_32x32x16_bf16 v[66:81], v[230:233], v[114:117], v[34:49]
	ds_read_b128 v[230:233], v0 offset:96
	v_add_f32_e32 v165, v95, v165
	v_add_f32_e32 v242, v96, v242
	v_add_f32_e32 v165, v97, v165
	v_add_f32_e32 v242, v166, v242
	s_waitcnt lgkmcnt(6)
	v_mfma_f32_32x32x16_bf16 v[66:81], v[234:237], v[118:121], v[66:81]
	ds_read_b128 v[234:237], v0 offset:13824
	v_add_f32_e32 v165, v167, v165
	v_add_f32_e32 v242, v168, v242
	v_add_f32_e32 v165, v169, v165
	v_add_f32_e32 v242, v170, v242
	s_waitcnt lgkmcnt(6)
	v_mfma_f32_32x32x16_bf16 v[66:81], v[238:241], v[122:125], v[66:81]
	ds_read_b128 v[238:241], v0 offset:13856
	v_add_f32_e32 v165, v171, v165
	v_add_f32_e32 v242, v172, v242
	v_add_f32_e32 v165, v173, v165
	v_add_f32_e32 v242, v174, v242
	v_max3_f32 v146, v50, v51, v52
	v_max3_f32 v146, v146, v53, v54
	s_waitcnt lgkmcnt(6)
	v_mfma_f32_32x32x16_bf16 v[66:81], v[214:217], v[126:129], v[66:81]
	ds_read_b128 v[214:217], v0 offset:13888
	v_add_f32_e32 v165, v175, v165
	v_add_f32_e32 v242, v176, v242
	v_add_f32_e32 v165, v177, v165
	v_add_f32_e32 v242, v178, v242
	v_max3_f32 v146, v146, v55, v56
	v_max3_f32 v146, v146, v57, v58
	s_waitcnt lgkmcnt(6)
	v_mfma_f32_32x32x16_bf16 v[98:113], v[218:221], v[114:117], v[34:49]
	ds_read_b128 v[218:221], v0 offset:13920
	v_add_f32_e32 v165, v179, v165
	v_add_f32_e32 v242, v191, v242
	v_add_f32_e32 v165, v192, v165
	v_add_f32_e32 v242, v193, v242
	v_max3_f32 v146, v146, v59, v60
	v_max3_f32 v146, v146, v61, v62
	s_waitcnt lgkmcnt(6)
	v_mfma_f32_32x32x16_bf16 v[98:113], v[222:225], v[118:121], v[98:113]
	ds_read_b128 v[206:209], v0 offset:36864
	v_add_f32_e32 v165, v194, v165
	v_add_f32_e32 v242, v195, v242
	v_add_f32_e32 v165, v196, v165
	v_add_f32_e32 v242, v197, v242
	v_max3_f32 v146, v146, v63, v64
	v_max3_f32 v146, v146, v65, v65
	s_waitcnt lgkmcnt(6)
	v_mfma_f32_32x32x16_bf16 v[98:113], v[226:229], v[122:125], v[98:113]
	ds_read_b128 v[210:213], v0 offset:41472
	v_add_f32_e32 v165, v198, v165
	v_add_f32_e32 v242, v199, v242
	v_add_f32_e32 v165, v200, v165
	v_add_f32_e32 v242, v201, v242
	v_max3_f32 v146, v146, v66, v67
	v_max3_f32 v146, v146, v68, v69
	s_waitcnt lgkmcnt(6)
	v_mfma_f32_32x32x16_bf16 v[98:113], v[230:233], v[126:129], v[98:113]
	ds_read_b128 v[222:225], v0 offset:36896
	v_add_f32_e32 v165, v202, v165
	v_add_f32_e32 v242, v203, v242
	v_add_f32_e32 v165, v204, v165
	v_add_f32_e32 v165, v242, v165
	v_max3_f32 v146, v146, v70, v71
	v_max3_f32 v146, v146, v72, v73
	s_waitcnt lgkmcnt(6)
	v_mfma_f32_32x32x16_bf16 v[82:97], v[234:237], v[114:117], v[34:49]
	ds_read_b128 v[226:229], v0 offset:41504
	v_max3_f32 v146, v146, v74, v75
	v_max3_f32 v146, v146, v76, v77
	s_waitcnt lgkmcnt(6)
	v_mfma_f32_32x32x16_bf16 v[82:97], v[238:241], v[118:121], v[82:97]
	ds_read_b128 v[230:233], v0 offset:36928
	v_max3_f32 v146, v146, v78, v79
	v_max3_f32 v146, v146, v80, v81
	s_waitcnt lgkmcnt(6)
	v_mfma_f32_32x32x16_bf16 v[82:97], v[214:217], v[122:125], v[82:97]
	ds_read_b128 v[234:237], v0 offset:41536
	s_waitcnt lgkmcnt(6)
	v_mfma_f32_32x32x16_bf16 v[82:97], v[218:221], v[126:129], v[82:97]
	v_max3_f32 v146, v146, v98, v99
	v_max3_f32 v146, v146, v100, v101
	v_max3_f32 v146, v146, v102, v103
	v_max3_f32 v146, v146, v104, v105
	v_max3_f32 v146, v146, v106, v107
	v_max3_f32 v146, v146, v108, v109
	v_max3_f32 v146, v146, v110, v111
	v_max3_f32 v146, v146, v112, v113
	s_nop 3
	v_max3_f32 v146, v146, v82, v83
	v_max3_f32 v146, v146, v84, v85
	v_max3_f32 v146, v146, v86, v87
	v_max3_f32 v146, v146, v88, v89
	v_max3_f32 v146, v146, v90, v91
	v_max3_f32 v146, v146, v92, v93
	v_max3_f32 v146, v146, v94, v95
	v_max3_f32 v146, v146, v96, v97
	v_mov_b32_e32 v147, v146
	s_nop 1
	v_permlane32_swap_b32_e32 v146, v147
	v_max_f32_e32 v147, v147, v147
	v_max_f32_e32 v146, v146, v146
	v_max_f32_e32 v146, v146, v147
	v_cmp_lt_f32_e32 vcc, s50, v146
	s_cbranch_vccz .LBB0_350
	v_max_f32_e32 v146, v146, v146
	v_max_f32_e32 v146, 0, v146
	v_exp_f32_e64 v148, -v146
	v_pk_add_f32 v[98:99], v[98:99], v[146:147] op_sel_hi:[1,0] neg_lo:[0,1] neg_hi:[0,1]
	v_pk_add_f32 v[66:67], v[66:67], v[146:147] op_sel_hi:[1,0] neg_lo:[0,1] neg_hi:[0,1]
	v_pk_add_f32 v[50:51], v[50:51], v[146:147] op_sel_hi:[1,0] neg_lo:[0,1] neg_hi:[0,1]
	v_mul_f32_e32 v165, v165, v148
	v_pk_mul_f32 v[16:17], v[16:17], v[148:149] op_sel_hi:[1,0]
	v_pk_mul_f32 v[14:15], v[14:15], v[148:149] op_sel_hi:[1,0]
	v_pk_mul_f32 v[12:13], v[12:13], v[148:149] op_sel_hi:[1,0]
	v_pk_mul_f32 v[10:11], v[10:11], v[148:149] op_sel_hi:[1,0]
	v_pk_mul_f32 v[8:9], v[8:9], v[148:149] op_sel_hi:[1,0]
	v_pk_mul_f32 v[6:7], v[6:7], v[148:149] op_sel_hi:[1,0]
	v_pk_mul_f32 v[4:5], v[4:5], v[148:149] op_sel_hi:[1,0]
	v_pk_mul_f32 v[2:3], v[2:3], v[148:149] op_sel_hi:[1,0]
	v_pk_mul_f32 v[32:33], v[32:33], v[148:149] op_sel_hi:[1,0]
	v_pk_mul_f32 v[30:31], v[30:31], v[148:149] op_sel_hi:[1,0]
	v_pk_mul_f32 v[28:29], v[28:29], v[148:149] op_sel_hi:[1,0]
	v_pk_mul_f32 v[26:27], v[26:27], v[148:149] op_sel_hi:[1,0]
	v_pk_mul_f32 v[24:25], v[24:25], v[148:149] op_sel_hi:[1,0]
	v_pk_mul_f32 v[22:23], v[22:23], v[148:149] op_sel_hi:[1,0]
	v_pk_mul_f32 v[20:21], v[20:21], v[148:149] op_sel_hi:[1,0]
	v_pk_mul_f32 v[18:19], v[18:19], v[148:149] op_sel_hi:[1,0]
	v_pk_add_f32 v[82:83], v[82:83], v[146:147] op_sel_hi:[1,0] neg_lo:[0,1] neg_hi:[0,1]
	v_pk_add_f32 v[100:101], v[100:101], v[146:147] op_sel_hi:[1,0] neg_lo:[0,1] neg_hi:[0,1]
	v_pk_add_f32 v[68:69], v[68:69], v[146:147] op_sel_hi:[1,0] neg_lo:[0,1] neg_hi:[0,1]
	v_pk_add_f32 v[52:53], v[52:53], v[146:147] op_sel_hi:[1,0] neg_lo:[0,1] neg_hi:[0,1]
	v_pk_add_f32 v[84:85], v[84:85], v[146:147] op_sel_hi:[1,0] neg_lo:[0,1] neg_hi:[0,1]
	v_pk_add_f32 v[102:103], v[102:103], v[146:147] op_sel_hi:[1,0] neg_lo:[0,1] neg_hi:[0,1]
	v_pk_add_f32 v[70:71], v[70:71], v[146:147] op_sel_hi:[1,0] neg_lo:[0,1] neg_hi:[0,1]
	v_pk_add_f32 v[54:55], v[54:55], v[146:147] op_sel_hi:[1,0] neg_lo:[0,1] neg_hi:[0,1]
	v_pk_add_f32 v[86:87], v[86:87], v[146:147] op_sel_hi:[1,0] neg_lo:[0,1] neg_hi:[0,1]
	v_pk_add_f32 v[104:105], v[104:105], v[146:147] op_sel_hi:[1,0] neg_lo:[0,1] neg_hi:[0,1]
	v_pk_add_f32 v[72:73], v[72:73], v[146:147] op_sel_hi:[1,0] neg_lo:[0,1] neg_hi:[0,1]
	v_pk_add_f32 v[56:57], v[56:57], v[146:147] op_sel_hi:[1,0] neg_lo:[0,1] neg_hi:[0,1]
	v_pk_add_f32 v[88:89], v[88:89], v[146:147] op_sel_hi:[1,0] neg_lo:[0,1] neg_hi:[0,1]
	v_pk_add_f32 v[106:107], v[106:107], v[146:147] op_sel_hi:[1,0] neg_lo:[0,1] neg_hi:[0,1]
	v_pk_add_f32 v[74:75], v[74:75], v[146:147] op_sel_hi:[1,0] neg_lo:[0,1] neg_hi:[0,1]
	v_pk_add_f32 v[58:59], v[58:59], v[146:147] op_sel_hi:[1,0] neg_lo:[0,1] neg_hi:[0,1]
	v_pk_add_f32 v[90:91], v[90:91], v[146:147] op_sel_hi:[1,0] neg_lo:[0,1] neg_hi:[0,1]
	v_pk_add_f32 v[108:109], v[108:109], v[146:147] op_sel_hi:[1,0] neg_lo:[0,1] neg_hi:[0,1]
	v_pk_add_f32 v[76:77], v[76:77], v[146:147] op_sel_hi:[1,0] neg_lo:[0,1] neg_hi:[0,1]
	v_pk_add_f32 v[60:61], v[60:61], v[146:147] op_sel_hi:[1,0] neg_lo:[0,1] neg_hi:[0,1]
	v_pk_add_f32 v[92:93], v[92:93], v[146:147] op_sel_hi:[1,0] neg_lo:[0,1] neg_hi:[0,1]
	v_pk_add_f32 v[110:111], v[110:111], v[146:147] op_sel_hi:[1,0] neg_lo:[0,1] neg_hi:[0,1]
	v_pk_add_f32 v[78:79], v[78:79], v[146:147] op_sel_hi:[1,0] neg_lo:[0,1] neg_hi:[0,1]
	v_pk_add_f32 v[62:63], v[62:63], v[146:147] op_sel_hi:[1,0] neg_lo:[0,1] neg_hi:[0,1]
	v_pk_add_f32 v[94:95], v[94:95], v[146:147] op_sel_hi:[1,0] neg_lo:[0,1] neg_hi:[0,1]
	v_pk_add_f32 v[112:113], v[112:113], v[146:147] op_sel_hi:[1,0] neg_lo:[0,1] neg_hi:[0,1]
	v_pk_add_f32 v[80:81], v[80:81], v[146:147] op_sel_hi:[1,0] neg_lo:[0,1] neg_hi:[0,1]
	v_pk_add_f32 v[64:65], v[64:65], v[146:147] op_sel_hi:[1,0] neg_lo:[0,1] neg_hi:[0,1]
	v_pk_add_f32 v[96:97], v[96:97], v[146:147] op_sel_hi:[1,0] neg_lo:[0,1] neg_hi:[0,1]
	v_sub_f32_e32 v49, v49, v146
	v_sub_f32_e32 v48, v48, v146
	v_sub_f32_e32 v47, v47, v146
	v_sub_f32_e32 v46, v46, v146
	v_sub_f32_e32 v45, v45, v146
	v_sub_f32_e32 v44, v44, v146
	v_sub_f32_e32 v43, v43, v146
	v_sub_f32_e32 v42, v42, v146
	v_sub_f32_e32 v41, v41, v146
	v_sub_f32_e32 v40, v40, v146
	v_sub_f32_e32 v39, v39, v146
	v_sub_f32_e32 v38, v38, v146
	v_sub_f32_e32 v37, v37, v146
	v_sub_f32_e32 v36, v36, v146
	v_sub_f32_e32 v35, v35, v146
	v_sub_f32_e32 v34, v34, v146
.LBB0_350:
	v_exp_f32_e32 v166, v98
	v_exp_f32_e32 v167, v99
	v_exp_f32_e32 v168, v100
	v_exp_f32_e32 v169, v101
	v_exp_f32_e32 v170, v102
	v_exp_f32_e32 v171, v103
	v_exp_f32_e32 v172, v104
	v_exp_f32_e32 v173, v105
	v_cvt_pk_bf16_f32 v146, v166, v167
	v_cvt_pk_bf16_f32 v147, v168, v169
	v_cvt_pk_bf16_f32 v148, v170, v171
	v_cvt_pk_bf16_f32 v149, v172, v173
	v_exp_f32_e32 v106, v106
	v_exp_f32_e32 v107, v107
	s_waitcnt lgkmcnt(5)
	v_mfma_f32_32x32x16_bf16 v[18:33], v[206:209], v[146:149], v[18:33]
	ds_read_b128 v[206:209], v0 offset:36960
	v_exp_f32_e32 v108, v108
	v_exp_f32_e32 v109, v109
	v_exp_f32_e32 v110, v110
	v_exp_f32_e32 v111, v111
	v_exp_f32_e32 v112, v112
	v_exp_f32_e32 v113, v113
	s_waitcnt lgkmcnt(5)
	v_mfma_f32_32x32x16_bf16 v[2:17], v[210:213], v[146:149], v[2:17]
	ds_read_b128 v[210:213], v0 offset:41568
	v_cvt_pk_bf16_f32 v102, v106, v107
	v_cvt_pk_bf16_f32 v103, v108, v109
	v_cvt_pk_bf16_f32 v104, v110, v111
	v_cvt_pk_bf16_f32 v105, v112, v113
	v_exp_f32_e32 v174, v66
	v_exp_f32_e32 v175, v67
	s_waitcnt lgkmcnt(5)
	v_mfma_f32_32x32x16_bf16 v[18:33], v[222:225], v[102:105], v[18:33]
	ds_read_b128 v[222:225], v0 offset:46080
	v_exp_f32_e32 v176, v68
	v_exp_f32_e32 v177, v69
	v_exp_f32_e32 v178, v70
	v_exp_f32_e32 v179, v71
	v_exp_f32_e32 v191, v72
	v_exp_f32_e32 v192, v73
	v_cvt_pk_bf16_f32 v98, v174, v175
	s_waitcnt lgkmcnt(5)
	v_mfma_f32_32x32x16_bf16 v[2:17], v[226:229], v[102:105], v[2:17]
	ds_read_b128 v[226:229], v0 offset:50688
	v_cvt_pk_bf16_f32 v99, v176, v177
	v_cvt_pk_bf16_f32 v100, v178, v179
	v_cvt_pk_bf16_f32 v101, v191, v192
	v_exp_f32_e32 v74, v74
	v_exp_f32_e32 v75, v75
	v_exp_f32_e32 v76, v76
	s_waitcnt lgkmcnt(5)
	v_mfma_f32_32x32x16_bf16 v[18:33], v[230:233], v[98:101], v[18:33]
	ds_read_b128 v[230:233], v0 offset:46112
	v_exp_f32_e32 v77, v77
	v_exp_f32_e32 v78, v78
	v_exp_f32_e32 v79, v79
	v_exp_f32_e32 v80, v80
	v_exp_f32_e32 v81, v81
	v_cvt_pk_bf16_f32 v70, v74, v75
	s_waitcnt lgkmcnt(5)
	v_mfma_f32_32x32x16_bf16 v[2:17], v[234:237], v[98:101], v[2:17]
	ds_read_b128 v[234:237], v0 offset:50720
	v_cvt_pk_bf16_f32 v71, v76, v77
	v_cvt_pk_bf16_f32 v72, v78, v79
	v_cvt_pk_bf16_f32 v73, v80, v81
	v_exp_f32_e32 v193, v50
	v_exp_f32_e32 v194, v51
	v_exp_f32_e32 v195, v52
	s_waitcnt lgkmcnt(5)
	v_mfma_f32_32x32x16_bf16 v[18:33], v[206:209], v[70:73], v[18:33]
	ds_read_b128 v[206:209], v0 offset:46144
	v_exp_f32_e32 v196, v53
	v_exp_f32_e32 v197, v54
	v_exp_f32_e32 v198, v55
	v_exp_f32_e32 v199, v56
	v_exp_f32_e32 v200, v57
	v_cvt_pk_bf16_f32 v66, v193, v194
	s_waitcnt lgkmcnt(5)
	v_mfma_f32_32x32x16_bf16 v[2:17], v[210:213], v[70:73], v[2:17]
	ds_read_b128 v[210:213], v0 offset:50752
	v_cvt_pk_bf16_f32 v67, v195, v196
	v_cvt_pk_bf16_f32 v68, v197, v198
	v_cvt_pk_bf16_f32 v69, v199, v200
	v_exp_f32_e32 v201, v58
	v_exp_f32_e32 v202, v59
	v_exp_f32_e32 v203, v60
	s_waitcnt lgkmcnt(5)
	v_mfma_f32_32x32x16_bf16 v[18:33], v[222:225], v[66:69], v[18:33]
	ds_read_b128 v[222:225], v0 offset:46176
	v_exp_f32_e32 v204, v61
	v_exp_f32_e32 v62, v62
	v_exp_f32_e32 v63, v63
	v_exp_f32_e32 v64, v64
	v_exp_f32_e32 v65, v65
	v_cvt_pk_bf16_f32 v58, v201, v202
	s_waitcnt lgkmcnt(5)
	v_mfma_f32_32x32x16_bf16 v[2:17], v[226:229], v[66:69], v[2:17]
	ds_read_b128 v[226:229], v0 offset:50784
	v_cvt_pk_bf16_f32 v59, v203, v204
	v_cvt_pk_bf16_f32 v60, v62, v63
	v_cvt_pk_bf16_f32 v61, v64, v65
	v_exp_f32_e32 v82, v82
	v_exp_f32_e32 v83, v83
	v_exp_f32_e32 v84, v84
	s_waitcnt lgkmcnt(5)
	v_mfma_f32_32x32x16_bf16 v[18:33], v[230:233], v[58:61], v[18:33]
	v_exp_f32_e32 v85, v85
	v_exp_f32_e32 v86, v86
	v_exp_f32_e32 v87, v87
	v_exp_f32_e32 v88, v88
	v_exp_f32_e32 v89, v89
	v_cvt_pk_bf16_f32 v54, v82, v83
	s_waitcnt lgkmcnt(4)
	v_mfma_f32_32x32x16_bf16 v[2:17], v[234:237], v[58:61], v[2:17]
	v_cvt_pk_bf16_f32 v55, v84, v85
	v_cvt_pk_bf16_f32 v56, v86, v87
	v_cvt_pk_bf16_f32 v57, v88, v89
	v_exp_f32_e32 v90, v90
	v_exp_f32_e32 v91, v91
	v_exp_f32_e32 v92, v92
	s_waitcnt lgkmcnt(3)
	v_mfma_f32_32x32x16_bf16 v[18:33], v[206:209], v[54:57], v[18:33]
	v_exp_f32_e32 v93, v93
	v_exp_f32_e32 v94, v94
	v_exp_f32_e32 v95, v95
	v_exp_f32_e32 v96, v96
	v_exp_f32_e32 v97, v97
	v_cvt_pk_bf16_f32 v50, v90, v91
	s_waitcnt lgkmcnt(2)
	v_mfma_f32_32x32x16_bf16 v[2:17], v[210:213], v[54:57], v[2:17]
	v_cvt_pk_bf16_f32 v51, v92, v93
	v_cvt_pk_bf16_f32 v52, v94, v95
	v_cvt_pk_bf16_f32 v53, v96, v97
	s_add_i32 s13, s12, -2
	s_cmp_ge_u32 s13, s23
	s_waitcnt lgkmcnt(1)
	v_mfma_f32_32x32x16_bf16 v[18:33], v[222:225], v[50:53], v[18:33]
	s_waitcnt lgkmcnt(0)
	v_mfma_f32_32x32x16_bf16 v[2:17], v[226:229], v[50:53], v[2:17]
	s_cbranch_scc1 .LBB0_356
	s_xor_b32 s14, s4, 2
	s_mulk_i32 s14, 0x2400
	s_and_saveexec_b64 s[4:5], s[0:1]
	s_cbranch_execz .LBB0_353
	v_add_u32_e32 v0, s14, v164
	s_waitcnt vmcnt(2)
	ds_write_b128 v0, v[130:133]

; DI unsigned pk2(float a, float b) { f32x2 v = {a, b}; return __builtin_bit_cast(unsigned, __builtin_convertvector(v, bf16x2_t)); }
;   DI void finish(f32x4 (&acc)[2][2][4][2], int tb, int q, int lane) {
;     ...
;         const int tok = tb + ai * 128 + m * 16 + fr;
;         float rc = 1.f;
;         if (GRP) rc = tab[512 + ((tb & 255) + ai * 128 + m * 16 + fr)];
;         float ss = 0.f;
;         const bool f32in = xin0 != nullptr, f32out = xout != nullptr;
;         const float* xs = (tok < NP_TOK) ? xin0 + (size_t)tok * 1024 : xin1 + (size_t)(tok - NP_TOK) * 1024;
; #pragma unroll
;         for (int b = 0; b < 2; ++b)
; #pragma unroll
;           for (int n = 0; n < 2; ++n) {
;             const int c = q * 64 + 32 * b + 16 * n + 4 * fq;
;             f32x4 xo4;
;             if (f32in) xo4 = *(const f32x4*)(xs + c);
;             else {
;               const u32x2 w = *(const u32x2*)(xb_in + (size_t)tok * 1024 + c);
;               xo4[0] = __uint_as_float(w.x << 16); xo4[1] = __uint_as_float(w.x & 0xffff0000u);
;               xo4[2] = __uint_as_float(w.y << 16); xo4[3] = __uint_as_float(w.y & 0xffff0000u);
;             }
;             f32x4 v = acc[ai][b][m][n];
;             if (GRP) v = v * rc;
;             f32x4 nv;
; #pragma unroll
;             for (int j = 0; j < 4; ++j) { nv[j] = xo4[j] + v[j]; ss += nv[j] * nv[j]; }
;             if (f32out) *(f32x4*)(xout + (size_t)tok * 1024 + c) = nv;
;             else { u32x2 w; w.x = pk2(nv[0], nv[1]); w.y = pk2(nv[2], nv[3]); *(u32x2*)(xb + (size_t)tok * 1024 + c) = w; }
.LBB0_666:
	v_mov_b32_e32 v144, v141
	s_lshl_b32 s0, s21, 8
	s_lshl_b32 s1, s20, 2
	s_add_i32 s0, s0, s30
	v_ashrrev_i32_e32 v0, 2, v144
	s_or_b32 s18, s1, s29
	v_and_b32_e32 v0, -4, v0
	v_and_or_b32 v132, v144, 15, s0
	v_lshl_add_u32 v130, s18, 6, v0
	s_mov_b32 s0, 0x8000
	v_cmp_gt_i32_e32 vcc, s0, v132
	v_ashrrev_i32_e32 v0, 31, v132
	v_readlane_b32 s0, v250, 52
	v_cndmask_b32_e32 v133, 0, v0, vcc
	v_lshlrev_b64 v[138:139], 11, v[132:133]
	v_readlane_b32 s1, v250, 53
	v_ashrrev_i32_e32 v131, 31, v130
	v_lshlrev_b64 v[134:135], 12, v[132:133]
	v_lshl_add_u64 v[136:137], s[0:1], 0, v[138:139]
	v_lshl_add_u64 v[136:137], v[130:131], 1, v[136:137]
	global_load_dwordx2 v[150:151], v[136:137], off
	global_load_dwordx2 v[152:153], v[136:137], off offset:32
	global_load_dwordx2 v[154:155], v[136:137], off offset:64
	global_load_dwordx2 v[156:157], v[136:137], off offset:96
	s_mov_b64 s[4:5], 0x8000
	v_lshl_add_u64 v[212:213], v[136:137], 0, s[4:5]
	global_load_dwordx2 v[158:159], v[212:213], off
	global_load_dwordx2 v[160:161], v[212:213], off offset:32
	global_load_dwordx2 v[162:163], v[212:213], off offset:64
	global_load_dwordx2 v[164:165], v[212:213], off offset:96
	s_mov_b64 s[4:5], 0x10000
	v_lshl_add_u64 v[212:213], v[136:137], 0, s[4:5]
	global_load_dwordx2 v[166:167], v[212:213], off
	global_load_dwordx2 v[168:169], v[212:213], off offset:32
	global_load_dwordx2 v[170:171], v[212:213], off offset:64
	global_load_dwordx2 v[172:173], v[212:213], off offset:96
	s_mov_b64 s[4:5], 0x18000
	v_lshl_add_u64 v[212:213], v[136:137], 0, s[4:5]
	global_load_dwordx2 v[174:175], v[212:213], off
	global_load_dwordx2 v[176:177], v[212:213], off offset:32
	global_load_dwordx2 v[178:179], v[212:213], off offset:64
	global_load_dwordx2 v[192:193], v[212:213], off offset:96
	s_mov_b64 s[4:5], 0x40000
	v_lshl_add_u64 v[212:213], v[136:137], 0, s[4:5]
	global_load_dwordx2 v[194:195], v[212:213], off
	global_load_dwordx2 v[196:197], v[212:213], off offset:32
	global_load_dwordx2 v[198:199], v[212:213], off offset:64
	global_load_dwordx2 v[200:201], v[212:213], off offset:96
	s_mov_b64 s[4:5], 0x48000
	v_lshl_add_u64 v[212:213], v[136:137], 0, s[4:5]
	global_load_dwordx2 v[202:203], v[212:213], off
	global_load_dwordx2 v[204:205], v[212:213], off offset:32
	global_load_dwordx2 v[206:207], v[212:213], off offset:64
	global_load_dwordx2 v[208:209], v[212:213], off offset:96
	s_mov_b64 s[4:5], 0x50000
	v_lshl_add_u64 v[212:213], v[136:137], 0, s[4:5]
	global_load_dwordx2 v[210:211], v[212:213], off
	global_load_dwordx2 v[214:215], v[212:213], off offset:32
	global_load_dwordx2 v[216:217], v[212:213], off offset:64
	global_load_dwordx2 v[218:219], v[212:213], off offset:96
	s_mov_b64 s[4:5], 0x58000
	v_lshl_add_u64 v[212:213], v[136:137], 0, s[4:5]
	global_load_dwordx2 v[220:221], v[212:213], off
	global_load_dwordx2 v[222:223], v[212:213], off offset:32
	global_load_dwordx2 v[224:225], v[212:213], off offset:64
	global_load_dwordx2 v[226:227], v[212:213], off offset:96
	v_cndmask_b32_e64 v0, 0, 1, s[10:11]
	v_lshl_add_u64 v[134:135], s[88:89], 0, v[134:135]
	v_readlane_b32 s76, v248, 5
	v_readlane_b32 s74, v248, 7
	s_mov_b64 s[4:5], -1
	v_cmp_ne_u32_e64 s[0:1], 1, v0
	s_andn2_b64 vcc, exec, s[10:11]
	v_lshl_add_u64 v[134:135], v[130:131], 2, v[134:135]
	v_readlane_b32 s77, v248, 6
	v_readlane_b32 s75, v248, 8
	s_waitcnt vmcnt(31)
	v_lshlrev_b32_e32 v148, 16, v150
	v_and_b32_e32 v149, 0xffff0000, v150
	v_lshlrev_b32_e32 v150, 16, v151
	v_and_b32_e32 v151, 0xffff0000, v151
	v_pk_add_f32 v[126:127], v[126:127], v[148:149]
	v_pk_add_f32 v[128:129], v[128:129], v[150:151]
	s_cbranch_vccnz .LBB0_668
	s_mov_b64 s[4:5], 0
	global_store_dwordx4 v[134:135], v[126:129], off

; DI unsigned pk2(float a, float b) { f32x2 v = {a, b}; return __builtin_bit_cast(unsigned, __builtin_convertvector(v, bf16x2_t)); }
;   DI void finish(f32x4 (&acc)[2][2][4][2], int tb, int q, int lane) {
;     ...
;             const int c = q * 64 + 32 * b + 16 * n + 4 * fq;
;             f32x4 xo4;
;             if (f32in) xo4 = *(const f32x4*)(xs + c);
;             else {
;               const u32x2 w = *(const u32x2*)(xb_in + (size_t)tok * 1024 + c);
;               xo4[0] = __uint_as_float(w.x << 16); xo4[1] = __uint_as_float(w.x & 0xffff0000u);
;               xo4[2] = __uint_as_float(w.y << 16); xo4[3] = __uint_as_float(w.y & 0xffff0000u);
;             }
;             f32x4 v = acc[ai][b][m][n];
;             if (GRP) v = v * rc;
;             f32x4 nv;
; #pragma unroll
;             for (int j = 0; j < 4; ++j) { nv[j] = xo4[j] + v[j]; ss += nv[j] * nv[j]; }
;             if (f32out) *(f32x4*)(xout + (size_t)tok * 1024 + c) = nv;
;             else { u32x2 w; w.x = pk2(nv[0], nv[1]); w.y = pk2(nv[2], nv[3]); *(u32x2*)(xb + (size_t)tok * 1024 + c) = w; }
.LBB0_670:
	v_readlane_b32 s64, v248, 3
	s_mov_b64 s[4:5], -1
	s_and_b64 vcc, exec, s[0:1]
	v_readlane_b32 s65, v248, 4
	s_waitcnt vmcnt(31)
	v_lshlrev_b32_e32 v148, 16, v152
	v_and_b32_e32 v149, 0xffff0000, v152
	v_lshlrev_b32_e32 v152, 16, v153
	v_and_b32_e32 v153, 0xffff0000, v153
	v_pk_add_f32 v[122:123], v[122:123], v[148:149]
	v_pk_add_f32 v[124:125], v[124:125], v[152:153]
	s_cbranch_vccnz .LBB0_672
	s_mov_b64 s[4:5], 0
	global_store_dwordx4 v[134:135], v[122:125], off offset:64

; DI unsigned pk2(float a, float b) { f32x2 v = {a, b}; return __builtin_bit_cast(unsigned, __builtin_convertvector(v, bf16x2_t)); }
;   DI void finish(f32x4 (&acc)[2][2][4][2], int tb, int q, int lane) {
;     ...
;             const int c = q * 64 + 32 * b + 16 * n + 4 * fq;
;             f32x4 xo4;
;             if (f32in) xo4 = *(const f32x4*)(xs + c);
;             else {
;               const u32x2 w = *(const u32x2*)(xb_in + (size_t)tok * 1024 + c);
;               xo4[0] = __uint_as_float(w.x << 16); xo4[1] = __uint_as_float(w.x & 0xffff0000u);
;               xo4[2] = __uint_as_float(w.y << 16); xo4[3] = __uint_as_float(w.y & 0xffff0000u);
;             }
;             f32x4 v = acc[ai][b][m][n];
;             if (GRP) v = v * rc;
;             f32x4 nv;
; #pragma unroll
;             for (int j = 0; j < 4; ++j) { nv[j] = xo4[j] + v[j]; ss += nv[j] * nv[j]; }
;             if (f32out) *(f32x4*)(xout + (size_t)tok * 1024 + c) = nv;
;             else { u32x2 w; w.x = pk2(nv[0], nv[1]); w.y = pk2(nv[2], nv[3]); *(u32x2*)(xb + (size_t)tok * 1024 + c) = w; }
.LBB0_674:
	s_mov_b64 s[4:5], -1
	s_and_b64 vcc, exec, s[0:1]
	s_waitcnt vmcnt(31)
	v_lshlrev_b32_e32 v148, 16, v154
	v_and_b32_e32 v149, 0xffff0000, v154
	v_lshlrev_b32_e32 v154, 16, v155
	v_and_b32_e32 v155, 0xffff0000, v155
	v_pk_add_f32 v[118:119], v[118:119], v[148:149]
	v_pk_add_f32 v[120:121], v[120:121], v[154:155]
	s_cbranch_vccnz .LBB0_676
	s_mov_b64 s[4:5], 0
	global_store_dwordx4 v[134:135], v[118:121], off offset:128

; DI unsigned pk2(float a, float b) { f32x2 v = {a, b}; return __builtin_bit_cast(unsigned, __builtin_convertvector(v, bf16x2_t)); }
;   DI void finish(f32x4 (&acc)[2][2][4][2], int tb, int q, int lane) {
;     ...
;             const int c = q * 64 + 32 * b + 16 * n + 4 * fq;
;             f32x4 xo4;
;             if (f32in) xo4 = *(const f32x4*)(xs + c);
;             else {
;               const u32x2 w = *(const u32x2*)(xb_in + (size_t)tok * 1024 + c);
;               xo4[0] = __uint_as_float(w.x << 16); xo4[1] = __uint_as_float(w.x & 0xffff0000u);
;               xo4[2] = __uint_as_float(w.y << 16); xo4[3] = __uint_as_float(w.y & 0xffff0000u);
;             }
;             f32x4 v = acc[ai][b][m][n];
;             if (GRP) v = v * rc;
;             f32x4 nv;
; #pragma unroll
;             for (int j = 0; j < 4; ++j) { nv[j] = xo4[j] + v[j]; ss += nv[j] * nv[j]; }
;             if (f32out) *(f32x4*)(xout + (size_t)tok * 1024 + c) = nv;
;             else { u32x2 w; w.x = pk2(nv[0], nv[1]); w.y = pk2(nv[2], nv[3]); *(u32x2*)(xb + (size_t)tok * 1024 + c) = w; }
.LBB0_678:
	s_mov_b64 s[4:5], -1
	s_and_b64 vcc, exec, s[0:1]
	s_waitcnt vmcnt(31)
	v_lshlrev_b32_e32 v146, 16, v156
	v_and_b32_e32 v147, 0xffff0000, v156
	v_lshlrev_b32_e32 v156, 16, v157
	v_and_b32_e32 v157, 0xffff0000, v157
	v_pk_add_f32 v[114:115], v[114:115], v[146:147]
	v_pk_add_f32 v[116:117], v[116:117], v[156:157]
	s_cbranch_vccnz .LBB0_680
	s_mov_b64 s[4:5], 0
	global_store_dwordx4 v[134:135], v[114:117], off offset:192

; DI unsigned pk2(float a, float b) { f32x2 v = {a, b}; return __builtin_bit_cast(unsigned, __builtin_convertvector(v, bf16x2_t)); }
;   DI void finish(f32x4 (&acc)[2][2][4][2], int tb, int q, int lane) {
;     ...
;         const int tok = tb + ai * 128 + m * 16 + fr;
;         float rc = 1.f;
;         if (GRP) rc = tab[512 + ((tb & 255) + ai * 128 + m * 16 + fr)];
;         float ss = 0.f;
;         const bool f32in = xin0 != nullptr, f32out = xout != nullptr;
;         const float* xs = (tok < NP_TOK) ? xin0 + (size_t)tok * 1024 : xin1 + (size_t)(tok - NP_TOK) * 1024;
; #pragma unroll
;         for (int b = 0; b < 2; ++b)
; #pragma unroll
;           for (int n = 0; n < 2; ++n) {
;             const int c = q * 64 + 32 * b + 16 * n + 4 * fq;
;             f32x4 xo4;
;             if (f32in) xo4 = *(const f32x4*)(xs + c);
;             else {
;               const u32x2 w = *(const u32x2*)(xb_in + (size_t)tok * 1024 + c);
;               xo4[0] = __uint_as_float(w.x << 16); xo4[1] = __uint_as_float(w.x & 0xffff0000u);
;               xo4[2] = __uint_as_float(w.y << 16); xo4[3] = __uint_as_float(w.y & 0xffff0000u);
;             }
;             f32x4 v = acc[ai][b][m][n];
;             if (GRP) v = v * rc;
;             f32x4 nv;
; #pragma unroll
;             for (int j = 0; j < 4; ++j) { nv[j] = xo4[j] + v[j]; ss += nv[j] * nv[j]; }
;             if (f32out) *(f32x4*)(xout + (size_t)tok * 1024 + c) = nv;
;             else { u32x2 w; w.x = pk2(nv[0], nv[1]); w.y = pk2(nv[2], nv[3]); *(u32x2*)(xb + (size_t)tok * 1024 + c) = w; }
.LBB0_684:
	s_or_b64 exec, exec, s[20:21]
	v_or_b32_e32 v114, 16, v132
	s_mov_b32 s20, 0x8000
	v_cmp_gt_i32_e32 vcc, s20, v114
	s_waitcnt lgkmcnt(0)
	v_ashrrev_i32_e32 v115, 31, v114
	v_readlane_b32 s20, v250, 52
	v_cndmask_b32_e32 v115, 0, v115, vcc
	v_lshlrev_b64 v[118:119], 11, v[114:115]
	v_readlane_b32 s21, v250, 53
	v_lshlrev_b64 v[116:117], 12, v[114:115]
	v_lshl_add_u64 v[116:117], s[88:89], 0, v[116:117]
	v_lshl_add_u64 v[120:121], s[20:21], 0, v[118:119]
	v_lshl_add_u64 v[120:121], v[130:131], 1, v[120:121]
	s_mov_b64 s[20:21], -1
	s_and_b64 vcc, exec, s[0:1]
	v_lshl_add_u64 v[116:117], v[130:131], 2, v[116:117]
	s_waitcnt vmcnt(31)
	v_lshlrev_b32_e32 v126, 16, v158
	v_and_b32_e32 v127, 0xffff0000, v158
	v_lshlrev_b32_e32 v158, 16, v159
	v_and_b32_e32 v159, 0xffff0000, v159
	v_pk_add_f32 v[110:111], v[110:111], v[126:127]
	v_pk_add_f32 v[112:113], v[112:113], v[158:159]
	s_cbranch_vccnz .LBB0_686
	s_mov_b64 s[20:21], 0
	global_store_dwordx4 v[116:117], v[110:113], off

; DI unsigned pk2(float a, float b) { f32x2 v = {a, b}; return __builtin_bit_cast(unsigned, __builtin_convertvector(v, bf16x2_t)); }
;   DI void finish(f32x4 (&acc)[2][2][4][2], int tb, int q, int lane) {
;     ...
;             const int c = q * 64 + 32 * b + 16 * n + 4 * fq;
;             f32x4 xo4;
;             if (f32in) xo4 = *(const f32x4*)(xs + c);
;             else {
;               const u32x2 w = *(const u32x2*)(xb_in + (size_t)tok * 1024 + c);
;               xo4[0] = __uint_as_float(w.x << 16); xo4[1] = __uint_as_float(w.x & 0xffff0000u);
;               xo4[2] = __uint_as_float(w.y << 16); xo4[3] = __uint_as_float(w.y & 0xffff0000u);
;             }
;             f32x4 v = acc[ai][b][m][n];
;             if (GRP) v = v * rc;
;             f32x4 nv;
; #pragma unroll
;             for (int j = 0; j < 4; ++j) { nv[j] = xo4[j] + v[j]; ss += nv[j] * nv[j]; }
;             if (f32out) *(f32x4*)(xout + (size_t)tok * 1024 + c) = nv;
;             else { u32x2 w; w.x = pk2(nv[0], nv[1]); w.y = pk2(nv[2], nv[3]); *(u32x2*)(xb + (size_t)tok * 1024 + c) = w; }
.LBB0_688:
	s_mov_b64 s[20:21], -1
	s_and_b64 vcc, exec, s[0:1]
	s_waitcnt vmcnt(31)
	v_lshlrev_b32_e32 v126, 16, v160
	v_and_b32_e32 v127, 0xffff0000, v160
	v_lshlrev_b32_e32 v160, 16, v161
	v_and_b32_e32 v161, 0xffff0000, v161
	v_pk_add_f32 v[106:107], v[106:107], v[126:127]
	v_pk_add_f32 v[108:109], v[108:109], v[160:161]
	s_cbranch_vccnz .LBB0_690
	s_mov_b64 s[20:21], 0
	global_store_dwordx4 v[116:117], v[106:109], off offset:64

; DI unsigned pk2(float a, float b) { f32x2 v = {a, b}; return __builtin_bit_cast(unsigned, __builtin_convertvector(v, bf16x2_t)); }
;   DI void finish(f32x4 (&acc)[2][2][4][2], int tb, int q, int lane) {
;     ...
;             const int c = q * 64 + 32 * b + 16 * n + 4 * fq;
;             f32x4 xo4;
;             if (f32in) xo4 = *(const f32x4*)(xs + c);
;             else {
;               const u32x2 w = *(const u32x2*)(xb_in + (size_t)tok * 1024 + c);
;               xo4[0] = __uint_as_float(w.x << 16); xo4[1] = __uint_as_float(w.x & 0xffff0000u);
;               xo4[2] = __uint_as_float(w.y << 16); xo4[3] = __uint_as_float(w.y & 0xffff0000u);
;             }
;             f32x4 v = acc[ai][b][m][n];
;             if (GRP) v = v * rc;
;             f32x4 nv;
; #pragma unroll
;             for (int j = 0; j < 4; ++j) { nv[j] = xo4[j] + v[j]; ss += nv[j] * nv[j]; }
;             if (f32out) *(f32x4*)(xout + (size_t)tok * 1024 + c) = nv;
;             else { u32x2 w; w.x = pk2(nv[0], nv[1]); w.y = pk2(nv[2], nv[3]); *(u32x2*)(xb + (size_t)tok * 1024 + c) = w; }
.LBB0_692:
	s_mov_b64 s[20:21], -1
	s_and_b64 vcc, exec, s[0:1]
	s_waitcnt vmcnt(31)
	v_lshlrev_b32_e32 v126, 16, v162
	v_and_b32_e32 v127, 0xffff0000, v162
	v_lshlrev_b32_e32 v162, 16, v163
	v_and_b32_e32 v163, 0xffff0000, v163
	v_pk_add_f32 v[102:103], v[102:103], v[126:127]
	v_pk_add_f32 v[104:105], v[104:105], v[162:163]
	s_cbranch_vccnz .LBB0_694
	s_mov_b64 s[20:21], 0
	global_store_dwordx4 v[116:117], v[102:105], off offset:128

; DI unsigned pk2(float a, float b) { f32x2 v = {a, b}; return __builtin_bit_cast(unsigned, __builtin_convertvector(v, bf16x2_t)); }
;   DI void finish(f32x4 (&acc)[2][2][4][2], int tb, int q, int lane) {
;     ...
;             const int c = q * 64 + 32 * b + 16 * n + 4 * fq;
;             f32x4 xo4;
;             if (f32in) xo4 = *(const f32x4*)(xs + c);
;             else {
;               const u32x2 w = *(const u32x2*)(xb_in + (size_t)tok * 1024 + c);
;               xo4[0] = __uint_as_float(w.x << 16); xo4[1] = __uint_as_float(w.x & 0xffff0000u);
;               xo4[2] = __uint_as_float(w.y << 16); xo4[3] = __uint_as_float(w.y & 0xffff0000u);
;             }
;             f32x4 v = acc[ai][b][m][n];
;             if (GRP) v = v * rc;
;             f32x4 nv;
; #pragma unroll
;             for (int j = 0; j < 4; ++j) { nv[j] = xo4[j] + v[j]; ss += nv[j] * nv[j]; }
;             if (f32out) *(f32x4*)(xout + (size_t)tok * 1024 + c) = nv;
;             else { u32x2 w; w.x = pk2(nv[0], nv[1]); w.y = pk2(nv[2], nv[3]); *(u32x2*)(xb + (size_t)tok * 1024 + c) = w; }
.LBB0_696:
	s_mov_b64 s[20:21], -1
	s_and_b64 vcc, exec, s[0:1]
	s_waitcnt vmcnt(31)
	v_lshlrev_b32_e32 v124, 16, v164
	v_and_b32_e32 v125, 0xffff0000, v164
	v_lshlrev_b32_e32 v164, 16, v165
	v_and_b32_e32 v165, 0xffff0000, v165
	v_pk_add_f32 v[98:99], v[98:99], v[124:125]
	v_pk_add_f32 v[100:101], v[100:101], v[164:165]
	s_cbranch_vccnz .LBB0_698
	s_mov_b64 s[20:21], 0
	global_store_dwordx4 v[116:117], v[98:101], off offset:192

; DI unsigned pk2(float a, float b) { f32x2 v = {a, b}; return __builtin_bit_cast(unsigned, __builtin_convertvector(v, bf16x2_t)); }
;   DI void finish(f32x4 (&acc)[2][2][4][2], int tb, int q, int lane) {
;     ...
;         const int tok = tb + ai * 128 + m * 16 + fr;
;         float rc = 1.f;
;         if (GRP) rc = tab[512 + ((tb & 255) + ai * 128 + m * 16 + fr)];
;         float ss = 0.f;
;         const bool f32in = xin0 != nullptr, f32out = xout != nullptr;
;         const float* xs = (tok < NP_TOK) ? xin0 + (size_t)tok * 1024 : xin1 + (size_t)(tok - NP_TOK) * 1024;
; #pragma unroll
;         for (int b = 0; b < 2; ++b)
; #pragma unroll
;           for (int n = 0; n < 2; ++n) {
;             const int c = q * 64 + 32 * b + 16 * n + 4 * fq;
;             f32x4 xo4;
;             if (f32in) xo4 = *(const f32x4*)(xs + c);
;             else {
;               const u32x2 w = *(const u32x2*)(xb_in + (size_t)tok * 1024 + c);
;               xo4[0] = __uint_as_float(w.x << 16); xo4[1] = __uint_as_float(w.x & 0xffff0000u);
;               xo4[2] = __uint_as_float(w.y << 16); xo4[3] = __uint_as_float(w.y & 0xffff0000u);
;             }
;             f32x4 v = acc[ai][b][m][n];
;             if (GRP) v = v * rc;
;             f32x4 nv;
; #pragma unroll
;             for (int j = 0; j < 4; ++j) { nv[j] = xo4[j] + v[j]; ss += nv[j] * nv[j]; }
;             if (f32out) *(f32x4*)(xout + (size_t)tok * 1024 + c) = nv;
;             else { u32x2 w; w.x = pk2(nv[0], nv[1]); w.y = pk2(nv[2], nv[3]); *(u32x2*)(xb + (size_t)tok * 1024 + c) = w; }
.LBB0_702:
	s_or_b64 exec, exec, s[20:21]
	v_or_b32_e32 v98, 32, v132
	s_mov_b32 s20, 0x8000
	v_cmp_gt_i32_e32 vcc, s20, v98
	s_waitcnt lgkmcnt(0)
	v_ashrrev_i32_e32 v99, 31, v98
	v_readlane_b32 s20, v250, 52
	v_cndmask_b32_e32 v99, 0, v99, vcc
	v_lshlrev_b64 v[102:103], 11, v[98:99]
	v_readlane_b32 s21, v250, 53
	v_lshlrev_b64 v[100:101], 12, v[98:99]
	v_lshl_add_u64 v[100:101], s[88:89], 0, v[100:101]
	v_lshl_add_u64 v[104:105], s[20:21], 0, v[102:103]
	v_lshl_add_u64 v[104:105], v[130:131], 1, v[104:105]
	s_mov_b64 s[20:21], -1
	s_and_b64 vcc, exec, s[0:1]
	v_lshl_add_u64 v[100:101], v[130:131], 2, v[100:101]
	s_waitcnt vmcnt(31)
	v_lshlrev_b32_e32 v108, 16, v166
	v_and_b32_e32 v109, 0xffff0000, v166
	v_lshlrev_b32_e32 v166, 16, v167
	v_and_b32_e32 v167, 0xffff0000, v167
	v_pk_add_f32 v[94:95], v[94:95], v[108:109]
	v_pk_add_f32 v[96:97], v[96:97], v[166:167]
	s_cbranch_vccnz .LBB0_704
	s_mov_b64 s[20:21], 0
	global_store_dwordx4 v[100:101], v[94:97], off

; DI unsigned pk2(float a, float b) { f32x2 v = {a, b}; return __builtin_bit_cast(unsigned, __builtin_convertvector(v, bf16x2_t)); }
;   DI void finish(f32x4 (&acc)[2][2][4][2], int tb, int q, int lane) {
;     ...
;             const int c = q * 64 + 32 * b + 16 * n + 4 * fq;
;             f32x4 xo4;
;             if (f32in) xo4 = *(const f32x4*)(xs + c);
;             else {
;               const u32x2 w = *(const u32x2*)(xb_in + (size_t)tok * 1024 + c);
;               xo4[0] = __uint_as_float(w.x << 16); xo4[1] = __uint_as_float(w.x & 0xffff0000u);
;               xo4[2] = __uint_as_float(w.y << 16); xo4[3] = __uint_as_float(w.y & 0xffff0000u);
;             }
;             f32x4 v = acc[ai][b][m][n];
;             if (GRP) v = v * rc;
;             f32x4 nv;
; #pragma unroll
;             for (int j = 0; j < 4; ++j) { nv[j] = xo4[j] + v[j]; ss += nv[j] * nv[j]; }
;             if (f32out) *(f32x4*)(xout + (size_t)tok * 1024 + c) = nv;
;             else { u32x2 w; w.x = pk2(nv[0], nv[1]); w.y = pk2(nv[2], nv[3]); *(u32x2*)(xb + (size_t)tok * 1024 + c) = w; }
.LBB0_706:
	s_mov_b64 s[20:21], -1
	s_and_b64 vcc, exec, s[0:1]
	s_waitcnt vmcnt(31)
	v_lshlrev_b32_e32 v108, 16, v168
	v_and_b32_e32 v109, 0xffff0000, v168
	v_lshlrev_b32_e32 v168, 16, v169
	v_and_b32_e32 v169, 0xffff0000, v169
	v_pk_add_f32 v[90:91], v[90:91], v[108:109]
	v_pk_add_f32 v[92:93], v[92:93], v[168:169]
	s_cbranch_vccnz .LBB0_708
	s_mov_b64 s[20:21], 0
	global_store_dwordx4 v[100:101], v[90:93], off offset:64

; DI unsigned pk2(float a, float b) { f32x2 v = {a, b}; return __builtin_bit_cast(unsigned, __builtin_convertvector(v, bf16x2_t)); }
;   DI void finish(f32x4 (&acc)[2][2][4][2], int tb, int q, int lane) {
;     ...
;             const int c = q * 64 + 32 * b + 16 * n + 4 * fq;
;             f32x4 xo4;
;             if (f32in) xo4 = *(const f32x4*)(xs + c);
;             else {
;               const u32x2 w = *(const u32x2*)(xb_in + (size_t)tok * 1024 + c);
;               xo4[0] = __uint_as_float(w.x << 16); xo4[1] = __uint_as_float(w.x & 0xffff0000u);
;               xo4[2] = __uint_as_float(w.y << 16); xo4[3] = __uint_as_float(w.y & 0xffff0000u);
;             }
;             f32x4 v = acc[ai][b][m][n];
;             if (GRP) v = v * rc;
;             f32x4 nv;
; #pragma unroll
;             for (int j = 0; j < 4; ++j) { nv[j] = xo4[j] + v[j]; ss += nv[j] * nv[j]; }
;             if (f32out) *(f32x4*)(xout + (size_t)tok * 1024 + c) = nv;
;             else { u32x2 w; w.x = pk2(nv[0], nv[1]); w.y = pk2(nv[2], nv[3]); *(u32x2*)(xb + (size_t)tok * 1024 + c) = w; }
.LBB0_710:
	s_mov_b64 s[20:21], -1
	s_and_b64 vcc, exec, s[0:1]
	s_waitcnt vmcnt(31)
	v_lshlrev_b32_e32 v108, 16, v170
	v_and_b32_e32 v109, 0xffff0000, v170
	v_lshlrev_b32_e32 v170, 16, v171
	v_and_b32_e32 v171, 0xffff0000, v171
	v_pk_add_f32 v[86:87], v[86:87], v[108:109]
	v_pk_add_f32 v[88:89], v[88:89], v[170:171]
	s_cbranch_vccnz .LBB0_712
	s_mov_b64 s[20:21], 0
	global_store_dwordx4 v[100:101], v[86:89], off offset:128

; DI unsigned pk2(float a, float b) { f32x2 v = {a, b}; return __builtin_bit_cast(unsigned, __builtin_convertvector(v, bf16x2_t)); }
;   DI void finish(f32x4 (&acc)[2][2][4][2], int tb, int q, int lane) {
;     ...
;             const int c = q * 64 + 32 * b + 16 * n + 4 * fq;
;             f32x4 xo4;
;             if (f32in) xo4 = *(const f32x4*)(xs + c);
;             else {
;               const u32x2 w = *(const u32x2*)(xb_in + (size_t)tok * 1024 + c);
;               xo4[0] = __uint_as_float(w.x << 16); xo4[1] = __uint_as_float(w.x & 0xffff0000u);
;               xo4[2] = __uint_as_float(w.y << 16); xo4[3] = __uint_as_float(w.y & 0xffff0000u);
;             }
;             f32x4 v = acc[ai][b][m][n];
;             if (GRP) v = v * rc;
;             f32x4 nv;
; #pragma unroll
;             for (int j = 0; j < 4; ++j) { nv[j] = xo4[j] + v[j]; ss += nv[j] * nv[j]; }
;             if (f32out) *(f32x4*)(xout + (size_t)tok * 1024 + c) = nv;
;             else { u32x2 w; w.x = pk2(nv[0], nv[1]); w.y = pk2(nv[2], nv[3]); *(u32x2*)(xb + (size_t)tok * 1024 + c) = w; }
.LBB0_714:
	s_mov_b64 s[20:21], -1
	s_and_b64 vcc, exec, s[0:1]
	s_waitcnt vmcnt(31)
	v_lshlrev_b32_e32 v106, 16, v172
	v_and_b32_e32 v107, 0xffff0000, v172
	v_lshlrev_b32_e32 v172, 16, v173
	v_and_b32_e32 v173, 0xffff0000, v173
	v_pk_add_f32 v[82:83], v[82:83], v[106:107]
	v_pk_add_f32 v[84:85], v[84:85], v[172:173]
	s_cbranch_vccnz .LBB0_716
	s_mov_b64 s[20:21], 0
	global_store_dwordx4 v[100:101], v[82:85], off offset:192

; DI unsigned pk2(float a, float b) { f32x2 v = {a, b}; return __builtin_bit_cast(unsigned, __builtin_convertvector(v, bf16x2_t)); }
;   DI void finish(f32x4 (&acc)[2][2][4][2], int tb, int q, int lane) {
;     ...
;         const int tok = tb + ai * 128 + m * 16 + fr;
;         float rc = 1.f;
;         if (GRP) rc = tab[512 + ((tb & 255) + ai * 128 + m * 16 + fr)];
;         float ss = 0.f;
;         const bool f32in = xin0 != nullptr, f32out = xout != nullptr;
;         const float* xs = (tok < NP_TOK) ? xin0 + (size_t)tok * 1024 : xin1 + (size_t)(tok - NP_TOK) * 1024;
; #pragma unroll
;         for (int b = 0; b < 2; ++b)
; #pragma unroll
;           for (int n = 0; n < 2; ++n) {
;             const int c = q * 64 + 32 * b + 16 * n + 4 * fq;
;             f32x4 xo4;
;             if (f32in) xo4 = *(const f32x4*)(xs + c);
;             else {
;               const u32x2 w = *(const u32x2*)(xb_in + (size_t)tok * 1024 + c);
;               xo4[0] = __uint_as_float(w.x << 16); xo4[1] = __uint_as_float(w.x & 0xffff0000u);
;               xo4[2] = __uint_as_float(w.y << 16); xo4[3] = __uint_as_float(w.y & 0xffff0000u);
;             }
;             f32x4 v = acc[ai][b][m][n];
;             if (GRP) v = v * rc;
;             f32x4 nv;
; #pragma unroll
;             for (int j = 0; j < 4; ++j) { nv[j] = xo4[j] + v[j]; ss += nv[j] * nv[j]; }
;             if (f32out) *(f32x4*)(xout + (size_t)tok * 1024 + c) = nv;
;             else { u32x2 w; w.x = pk2(nv[0], nv[1]); w.y = pk2(nv[2], nv[3]); *(u32x2*)(xb + (size_t)tok * 1024 + c) = w; }
.LBB0_720:
	s_or_b64 exec, exec, s[20:21]
	v_or_b32_e32 v82, 48, v132
	s_mov_b32 s20, 0x8000
	v_cmp_gt_i32_e32 vcc, s20, v82
	s_waitcnt lgkmcnt(0)
	v_ashrrev_i32_e32 v83, 31, v82
	v_readlane_b32 s20, v250, 52
	v_cndmask_b32_e32 v83, 0, v83, vcc
	v_lshlrev_b64 v[86:87], 11, v[82:83]
	v_readlane_b32 s21, v250, 53
	v_lshlrev_b64 v[84:85], 12, v[82:83]
	v_lshl_add_u64 v[84:85], s[88:89], 0, v[84:85]
	v_lshl_add_u64 v[88:89], s[20:21], 0, v[86:87]
	v_lshl_add_u64 v[88:89], v[130:131], 1, v[88:89]
	s_mov_b64 s[20:21], -1
	s_and_b64 vcc, exec, s[0:1]
	v_lshl_add_u64 v[84:85], v[130:131], 2, v[84:85]
	s_waitcnt vmcnt(31)
	v_lshlrev_b32_e32 v92, 16, v174
	v_and_b32_e32 v93, 0xffff0000, v174
	v_lshlrev_b32_e32 v174, 16, v175
	v_and_b32_e32 v175, 0xffff0000, v175
	v_pk_add_f32 v[78:79], v[78:79], v[92:93]
	v_pk_add_f32 v[80:81], v[80:81], v[174:175]
	s_cbranch_vccnz .LBB0_722
	s_mov_b64 s[20:21], 0
	global_store_dwordx4 v[84:85], v[78:81], off

; DI unsigned pk2(float a, float b) { f32x2 v = {a, b}; return __builtin_bit_cast(unsigned, __builtin_convertvector(v, bf16x2_t)); }
;   DI void finish(f32x4 (&acc)[2][2][4][2], int tb, int q, int lane) {
;     ...
;             const int c = q * 64 + 32 * b + 16 * n + 4 * fq;
;             f32x4 xo4;
;             if (f32in) xo4 = *(const f32x4*)(xs + c);
;             else {
;               const u32x2 w = *(const u32x2*)(xb_in + (size_t)tok * 1024 + c);
;               xo4[0] = __uint_as_float(w.x << 16); xo4[1] = __uint_as_float(w.x & 0xffff0000u);
;               xo4[2] = __uint_as_float(w.y << 16); xo4[3] = __uint_as_float(w.y & 0xffff0000u);
;             }
;             f32x4 v = acc[ai][b][m][n];
;             if (GRP) v = v * rc;
;             f32x4 nv;
; #pragma unroll
;             for (int j = 0; j < 4; ++j) { nv[j] = xo4[j] + v[j]; ss += nv[j] * nv[j]; }
;             if (f32out) *(f32x4*)(xout + (size_t)tok * 1024 + c) = nv;
;             else { u32x2 w; w.x = pk2(nv[0], nv[1]); w.y = pk2(nv[2], nv[3]); *(u32x2*)(xb + (size_t)tok * 1024 + c) = w; }
.LBB0_724:
	s_mov_b64 s[20:21], -1
	s_and_b64 vcc, exec, s[0:1]
	s_waitcnt vmcnt(31)
	v_lshlrev_b32_e32 v92, 16, v176
	v_and_b32_e32 v93, 0xffff0000, v176
	v_lshlrev_b32_e32 v176, 16, v177
	v_and_b32_e32 v177, 0xffff0000, v177
	v_pk_add_f32 v[74:75], v[74:75], v[92:93]
	v_pk_add_f32 v[76:77], v[76:77], v[176:177]
	s_cbranch_vccnz .LBB0_726
	s_mov_b64 s[20:21], 0
	global_store_dwordx4 v[84:85], v[74:77], off offset:64

; DI unsigned pk2(float a, float b) { f32x2 v = {a, b}; return __builtin_bit_cast(unsigned, __builtin_convertvector(v, bf16x2_t)); }
;   DI void finish(f32x4 (&acc)[2][2][4][2], int tb, int q, int lane) {
;     ...
;             const int c = q * 64 + 32 * b + 16 * n + 4 * fq;
;             f32x4 xo4;
;             if (f32in) xo4 = *(const f32x4*)(xs + c);
;             else {
;               const u32x2 w = *(const u32x2*)(xb_in + (size_t)tok * 1024 + c);
;               xo4[0] = __uint_as_float(w.x << 16); xo4[1] = __uint_as_float(w.x & 0xffff0000u);
;               xo4[2] = __uint_as_float(w.y << 16); xo4[3] = __uint_as_float(w.y & 0xffff0000u);
;             }
;             f32x4 v = acc[ai][b][m][n];
;             if (GRP) v = v * rc;
;             f32x4 nv;
; #pragma unroll
;             for (int j = 0; j < 4; ++j) { nv[j] = xo4[j] + v[j]; ss += nv[j] * nv[j]; }
;             if (f32out) *(f32x4*)(xout + (size_t)tok * 1024 + c) = nv;
;             else { u32x2 w; w.x = pk2(nv[0], nv[1]); w.y = pk2(nv[2], nv[3]); *(u32x2*)(xb + (size_t)tok * 1024 + c) = w; }
.LBB0_728:
	s_mov_b64 s[20:21], -1
	s_and_b64 vcc, exec, s[0:1]
	s_waitcnt vmcnt(31)
	v_lshlrev_b32_e32 v92, 16, v178
	v_and_b32_e32 v93, 0xffff0000, v178
	v_lshlrev_b32_e32 v178, 16, v179
	v_and_b32_e32 v179, 0xffff0000, v179
	v_pk_add_f32 v[70:71], v[70:71], v[92:93]
	v_pk_add_f32 v[72:73], v[72:73], v[178:179]
	s_cbranch_vccnz .LBB0_730
	s_mov_b64 s[20:21], 0
	global_store_dwordx4 v[84:85], v[70:73], off offset:128

; DI unsigned pk2(float a, float b) { f32x2 v = {a, b}; return __builtin_bit_cast(unsigned, __builtin_convertvector(v, bf16x2_t)); }
;   DI void finish(f32x4 (&acc)[2][2][4][2], int tb, int q, int lane) {
;     ...
;             const int c = q * 64 + 32 * b + 16 * n + 4 * fq;
;             f32x4 xo4;
;             if (f32in) xo4 = *(const f32x4*)(xs + c);
;             else {
;               const u32x2 w = *(const u32x2*)(xb_in + (size_t)tok * 1024 + c);
;               xo4[0] = __uint_as_float(w.x << 16); xo4[1] = __uint_as_float(w.x & 0xffff0000u);
;               xo4[2] = __uint_as_float(w.y << 16); xo4[3] = __uint_as_float(w.y & 0xffff0000u);
;             }
;             f32x4 v = acc[ai][b][m][n];
;             if (GRP) v = v * rc;
;             f32x4 nv;
; #pragma unroll
;             for (int j = 0; j < 4; ++j) { nv[j] = xo4[j] + v[j]; ss += nv[j] * nv[j]; }
;             if (f32out) *(f32x4*)(xout + (size_t)tok * 1024 + c) = nv;
;             else { u32x2 w; w.x = pk2(nv[0], nv[1]); w.y = pk2(nv[2], nv[3]); *(u32x2*)(xb + (size_t)tok * 1024 + c) = w; }
.LBB0_732:
	s_mov_b64 s[20:21], -1
	s_and_b64 vcc, exec, s[0:1]
	s_waitcnt vmcnt(31)
	v_lshlrev_b32_e32 v90, 16, v192
	v_and_b32_e32 v91, 0xffff0000, v192
	v_lshlrev_b32_e32 v192, 16, v193
	v_and_b32_e32 v193, 0xffff0000, v193
	v_pk_add_f32 v[66:67], v[66:67], v[90:91]
	v_pk_add_f32 v[68:69], v[68:69], v[192:193]
	s_cbranch_vccnz .LBB0_734
	s_mov_b64 s[20:21], 0
	global_store_dwordx4 v[84:85], v[66:69], off offset:192

; DI unsigned pk2(float a, float b) { f32x2 v = {a, b}; return __builtin_bit_cast(unsigned, __builtin_convertvector(v, bf16x2_t)); }
;   DI void finish(f32x4 (&acc)[2][2][4][2], int tb, int q, int lane) {
;     ...
;         const int tok = tb + ai * 128 + m * 16 + fr;
;         float rc = 1.f;
;         if (GRP) rc = tab[512 + ((tb & 255) + ai * 128 + m * 16 + fr)];
;         float ss = 0.f;
;         const bool f32in = xin0 != nullptr, f32out = xout != nullptr;
;         const float* xs = (tok < NP_TOK) ? xin0 + (size_t)tok * 1024 : xin1 + (size_t)(tok - NP_TOK) * 1024;
; #pragma unroll
;         for (int b = 0; b < 2; ++b)
; #pragma unroll
;           for (int n = 0; n < 2; ++n) {
;             const int c = q * 64 + 32 * b + 16 * n + 4 * fq;
;             f32x4 xo4;
;             if (f32in) xo4 = *(const f32x4*)(xs + c);
;             else {
;               const u32x2 w = *(const u32x2*)(xb_in + (size_t)tok * 1024 + c);
;               xo4[0] = __uint_as_float(w.x << 16); xo4[1] = __uint_as_float(w.x & 0xffff0000u);
;               xo4[2] = __uint_as_float(w.y << 16); xo4[3] = __uint_as_float(w.y & 0xffff0000u);
;             }
;             f32x4 v = acc[ai][b][m][n];
;             if (GRP) v = v * rc;
;             f32x4 nv;
; #pragma unroll
;             for (int j = 0; j < 4; ++j) { nv[j] = xo4[j] + v[j]; ss += nv[j] * nv[j]; }
;             if (f32out) *(f32x4*)(xout + (size_t)tok * 1024 + c) = nv;
;             else { u32x2 w; w.x = pk2(nv[0], nv[1]); w.y = pk2(nv[2], nv[3]); *(u32x2*)(xb + (size_t)tok * 1024 + c) = w; }
.LBB0_738:
	s_or_b64 exec, exec, s[20:21]
	v_add_u32_e32 v66, 0x80, v132
	s_mov_b32 s20, 0x8000
	v_cmp_gt_i32_e32 vcc, s20, v66
	s_waitcnt lgkmcnt(0)
	v_ashrrev_i32_e32 v67, 31, v66
	v_readlane_b32 s20, v250, 52
	v_cndmask_b32_e32 v67, 0, v67, vcc
	v_lshlrev_b64 v[70:71], 11, v[66:67]
	v_readlane_b32 s21, v250, 53
	v_lshlrev_b64 v[68:69], 12, v[66:67]
	v_lshl_add_u64 v[68:69], s[88:89], 0, v[68:69]
	v_lshl_add_u64 v[72:73], s[20:21], 0, v[70:71]
	v_lshl_add_u64 v[72:73], v[130:131], 1, v[72:73]
	s_mov_b64 s[20:21], -1
	s_and_b64 vcc, exec, s[0:1]
	v_lshl_add_u64 v[68:69], v[130:131], 2, v[68:69]
	s_waitcnt vmcnt(31)
	v_lshlrev_b32_e32 v76, 16, v194
	v_and_b32_e32 v77, 0xffff0000, v194
	v_lshlrev_b32_e32 v194, 16, v195
	v_and_b32_e32 v195, 0xffff0000, v195
	v_pk_add_f32 v[62:63], v[62:63], v[76:77]
	v_pk_add_f32 v[64:65], v[64:65], v[194:195]
	s_cbranch_vccnz .LBB0_740
	s_mov_b64 s[20:21], 0
	global_store_dwordx4 v[68:69], v[62:65], off

; DI unsigned pk2(float a, float b) { f32x2 v = {a, b}; return __builtin_bit_cast(unsigned, __builtin_convertvector(v, bf16x2_t)); }
;   DI void finish(f32x4 (&acc)[2][2][4][2], int tb, int q, int lane) {
;     ...
;             const int c = q * 64 + 32 * b + 16 * n + 4 * fq;
;             f32x4 xo4;
;             if (f32in) xo4 = *(const f32x4*)(xs + c);
;             else {
;               const u32x2 w = *(const u32x2*)(xb_in + (size_t)tok * 1024 + c);
;               xo4[0] = __uint_as_float(w.x << 16); xo4[1] = __uint_as_float(w.x & 0xffff0000u);
;               xo4[2] = __uint_as_float(w.y << 16); xo4[3] = __uint_as_float(w.y & 0xffff0000u);
;             }
;             f32x4 v = acc[ai][b][m][n];
;             if (GRP) v = v * rc;
;             f32x4 nv;
; #pragma unroll
;             for (int j = 0; j < 4; ++j) { nv[j] = xo4[j] + v[j]; ss += nv[j] * nv[j]; }
;             if (f32out) *(f32x4*)(xout + (size_t)tok * 1024 + c) = nv;
;             else { u32x2 w; w.x = pk2(nv[0], nv[1]); w.y = pk2(nv[2], nv[3]); *(u32x2*)(xb + (size_t)tok * 1024 + c) = w; }
.LBB0_742:
	s_mov_b64 s[20:21], -1
	s_and_b64 vcc, exec, s[0:1]
	s_waitcnt vmcnt(31)
	v_lshlrev_b32_e32 v76, 16, v196
	v_and_b32_e32 v77, 0xffff0000, v196
	v_lshlrev_b32_e32 v196, 16, v197
	v_and_b32_e32 v197, 0xffff0000, v197
	v_pk_add_f32 v[58:59], v[58:59], v[76:77]
	v_pk_add_f32 v[60:61], v[60:61], v[196:197]
	s_cbranch_vccnz .LBB0_744
	s_mov_b64 s[20:21], 0
	global_store_dwordx4 v[68:69], v[58:61], off offset:64

; DI unsigned pk2(float a, float b) { f32x2 v = {a, b}; return __builtin_bit_cast(unsigned, __builtin_convertvector(v, bf16x2_t)); }
;   DI void finish(f32x4 (&acc)[2][2][4][2], int tb, int q, int lane) {
;     ...
;             const int c = q * 64 + 32 * b + 16 * n + 4 * fq;
;             f32x4 xo4;
;             if (f32in) xo4 = *(const f32x4*)(xs + c);
;             else {
;               const u32x2 w = *(const u32x2*)(xb_in + (size_t)tok * 1024 + c);
;               xo4[0] = __uint_as_float(w.x << 16); xo4[1] = __uint_as_float(w.x & 0xffff0000u);
;               xo4[2] = __uint_as_float(w.y << 16); xo4[3] = __uint_as_float(w.y & 0xffff0000u);
;             }
;             f32x4 v = acc[ai][b][m][n];
;             if (GRP) v = v * rc;
;             f32x4 nv;
; #pragma unroll
;             for (int j = 0; j < 4; ++j) { nv[j] = xo4[j] + v[j]; ss += nv[j] * nv[j]; }
;             if (f32out) *(f32x4*)(xout + (size_t)tok * 1024 + c) = nv;
;             else { u32x2 w; w.x = pk2(nv[0], nv[1]); w.y = pk2(nv[2], nv[3]); *(u32x2*)(xb + (size_t)tok * 1024 + c) = w; }
.LBB0_746:
	s_mov_b64 s[20:21], -1
	s_and_b64 vcc, exec, s[0:1]
	s_waitcnt vmcnt(31)
	v_lshlrev_b32_e32 v76, 16, v198
	v_and_b32_e32 v77, 0xffff0000, v198
	v_lshlrev_b32_e32 v198, 16, v199
	v_and_b32_e32 v199, 0xffff0000, v199
	v_pk_add_f32 v[54:55], v[54:55], v[76:77]
	v_pk_add_f32 v[56:57], v[56:57], v[198:199]
	s_cbranch_vccnz .LBB0_748
	s_mov_b64 s[20:21], 0
	global_store_dwordx4 v[68:69], v[54:57], off offset:128

; DI unsigned pk2(float a, float b) { f32x2 v = {a, b}; return __builtin_bit_cast(unsigned, __builtin_convertvector(v, bf16x2_t)); }
;   DI void finish(f32x4 (&acc)[2][2][4][2], int tb, int q, int lane) {
;     ...
;             const int c = q * 64 + 32 * b + 16 * n + 4 * fq;
;             f32x4 xo4;
;             if (f32in) xo4 = *(const f32x4*)(xs + c);
;             else {
;               const u32x2 w = *(const u32x2*)(xb_in + (size_t)tok * 1024 + c);
;               xo4[0] = __uint_as_float(w.x << 16); xo4[1] = __uint_as_float(w.x & 0xffff0000u);
;               xo4[2] = __uint_as_float(w.y << 16); xo4[3] = __uint_as_float(w.y & 0xffff0000u);
;             }
;             f32x4 v = acc[ai][b][m][n];
;             if (GRP) v = v * rc;
;             f32x4 nv;
; #pragma unroll
;             for (int j = 0; j < 4; ++j) { nv[j] = xo4[j] + v[j]; ss += nv[j] * nv[j]; }
;             if (f32out) *(f32x4*)(xout + (size_t)tok * 1024 + c) = nv;
;             else { u32x2 w; w.x = pk2(nv[0], nv[1]); w.y = pk2(nv[2], nv[3]); *(u32x2*)(xb + (size_t)tok * 1024 + c) = w; }
.LBB0_750:
	s_mov_b64 s[20:21], -1
	s_and_b64 vcc, exec, s[0:1]
	s_waitcnt vmcnt(31)
	v_lshlrev_b32_e32 v74, 16, v200
	v_and_b32_e32 v75, 0xffff0000, v200
	v_lshlrev_b32_e32 v200, 16, v201
	v_and_b32_e32 v201, 0xffff0000, v201
	v_pk_add_f32 v[50:51], v[50:51], v[74:75]
	v_pk_add_f32 v[52:53], v[52:53], v[200:201]
	s_cbranch_vccnz .LBB0_752
	s_mov_b64 s[20:21], 0
	global_store_dwordx4 v[68:69], v[50:53], off offset:192

; DI unsigned pk2(float a, float b) { f32x2 v = {a, b}; return __builtin_bit_cast(unsigned, __builtin_convertvector(v, bf16x2_t)); }
;   DI void finish(f32x4 (&acc)[2][2][4][2], int tb, int q, int lane) {
;     ...
;         const int tok = tb + ai * 128 + m * 16 + fr;
;         float rc = 1.f;
;         if (GRP) rc = tab[512 + ((tb & 255) + ai * 128 + m * 16 + fr)];
;         float ss = 0.f;
;         const bool f32in = xin0 != nullptr, f32out = xout != nullptr;
;         const float* xs = (tok < NP_TOK) ? xin0 + (size_t)tok * 1024 : xin1 + (size_t)(tok - NP_TOK) * 1024;
; #pragma unroll
;         for (int b = 0; b < 2; ++b)
; #pragma unroll
;           for (int n = 0; n < 2; ++n) {
;             const int c = q * 64 + 32 * b + 16 * n + 4 * fq;
;             f32x4 xo4;
;             if (f32in) xo4 = *(const f32x4*)(xs + c);
;             else {
;               const u32x2 w = *(const u32x2*)(xb_in + (size_t)tok * 1024 + c);
;               xo4[0] = __uint_as_float(w.x << 16); xo4[1] = __uint_as_float(w.x & 0xffff0000u);
;               xo4[2] = __uint_as_float(w.y << 16); xo4[3] = __uint_as_float(w.y & 0xffff0000u);
;             }
;             f32x4 v = acc[ai][b][m][n];
;             if (GRP) v = v * rc;
;             f32x4 nv;
; #pragma unroll
;             for (int j = 0; j < 4; ++j) { nv[j] = xo4[j] + v[j]; ss += nv[j] * nv[j]; }
;             if (f32out) *(f32x4*)(xout + (size_t)tok * 1024 + c) = nv;
;             else { u32x2 w; w.x = pk2(nv[0], nv[1]); w.y = pk2(nv[2], nv[3]); *(u32x2*)(xb + (size_t)tok * 1024 + c) = w; }
.LBB0_756:
	s_or_b64 exec, exec, s[20:21]
	v_add_u32_e32 v50, 0x90, v132
	s_mov_b32 s20, 0x8000
	v_cmp_gt_i32_e32 vcc, s20, v50
	s_waitcnt lgkmcnt(0)
	v_ashrrev_i32_e32 v51, 31, v50
	v_readlane_b32 s20, v250, 52
	v_cndmask_b32_e32 v51, 0, v51, vcc
	v_lshlrev_b64 v[54:55], 11, v[50:51]
	v_readlane_b32 s21, v250, 53
	v_lshlrev_b64 v[52:53], 12, v[50:51]
	v_lshl_add_u64 v[52:53], s[88:89], 0, v[52:53]
	v_lshl_add_u64 v[56:57], s[20:21], 0, v[54:55]
	v_lshl_add_u64 v[56:57], v[130:131], 1, v[56:57]
	s_mov_b64 s[20:21], -1
	s_and_b64 vcc, exec, s[0:1]
	v_lshl_add_u64 v[52:53], v[130:131], 2, v[52:53]
	s_waitcnt vmcnt(31)
	v_lshlrev_b32_e32 v60, 16, v202
	v_and_b32_e32 v61, 0xffff0000, v202
	v_lshlrev_b32_e32 v202, 16, v203
	v_and_b32_e32 v203, 0xffff0000, v203
	v_pk_add_f32 v[46:47], v[46:47], v[60:61]
	v_pk_add_f32 v[48:49], v[48:49], v[202:203]
	s_cbranch_vccnz .LBB0_758
	s_mov_b64 s[20:21], 0
	global_store_dwordx4 v[52:53], v[46:49], off

; DI unsigned pk2(float a, float b) { f32x2 v = {a, b}; return __builtin_bit_cast(unsigned, __builtin_convertvector(v, bf16x2_t)); }
;   DI void finish(f32x4 (&acc)[2][2][4][2], int tb, int q, int lane) {
;     ...
;             const int c = q * 64 + 32 * b + 16 * n + 4 * fq;
;             f32x4 xo4;
;             if (f32in) xo4 = *(const f32x4*)(xs + c);
;             else {
;               const u32x2 w = *(const u32x2*)(xb_in + (size_t)tok * 1024 + c);
;               xo4[0] = __uint_as_float(w.x << 16); xo4[1] = __uint_as_float(w.x & 0xffff0000u);
;               xo4[2] = __uint_as_float(w.y << 16); xo4[3] = __uint_as_float(w.y & 0xffff0000u);
;             }
;             f32x4 v = acc[ai][b][m][n];
;             if (GRP) v = v * rc;
;             f32x4 nv;
; #pragma unroll
;             for (int j = 0; j < 4; ++j) { nv[j] = xo4[j] + v[j]; ss += nv[j] * nv[j]; }
;             if (f32out) *(f32x4*)(xout + (size_t)tok * 1024 + c) = nv;
;             else { u32x2 w; w.x = pk2(nv[0], nv[1]); w.y = pk2(nv[2], nv[3]); *(u32x2*)(xb + (size_t)tok * 1024 + c) = w; }
.LBB0_760:
	s_mov_b64 s[20:21], -1
	s_and_b64 vcc, exec, s[0:1]
	s_waitcnt vmcnt(31)
	v_lshlrev_b32_e32 v60, 16, v204
	v_and_b32_e32 v61, 0xffff0000, v204
	v_lshlrev_b32_e32 v204, 16, v205
	v_and_b32_e32 v205, 0xffff0000, v205
	v_pk_add_f32 v[42:43], v[42:43], v[60:61]
	v_pk_add_f32 v[44:45], v[44:45], v[204:205]
	s_cbranch_vccnz .LBB0_762
	s_mov_b64 s[20:21], 0
	global_store_dwordx4 v[52:53], v[42:45], off offset:64

; DI unsigned pk2(float a, float b) { f32x2 v = {a, b}; return __builtin_bit_cast(unsigned, __builtin_convertvector(v, bf16x2_t)); }
;   DI void finish(f32x4 (&acc)[2][2][4][2], int tb, int q, int lane) {
;     ...
;             const int c = q * 64 + 32 * b + 16 * n + 4 * fq;
;             f32x4 xo4;
;             if (f32in) xo4 = *(const f32x4*)(xs + c);
;             else {
;               const u32x2 w = *(const u32x2*)(xb_in + (size_t)tok * 1024 + c);
;               xo4[0] = __uint_as_float(w.x << 16); xo4[1] = __uint_as_float(w.x & 0xffff0000u);
;               xo4[2] = __uint_as_float(w.y << 16); xo4[3] = __uint_as_float(w.y & 0xffff0000u);
;             }
;             f32x4 v = acc[ai][b][m][n];
;             if (GRP) v = v * rc;
;             f32x4 nv;
; #pragma unroll
;             for (int j = 0; j < 4; ++j) { nv[j] = xo4[j] + v[j]; ss += nv[j] * nv[j]; }
;             if (f32out) *(f32x4*)(xout + (size_t)tok * 1024 + c) = nv;
;             else { u32x2 w; w.x = pk2(nv[0], nv[1]); w.y = pk2(nv[2], nv[3]); *(u32x2*)(xb + (size_t)tok * 1024 + c) = w; }
.LBB0_764:
	s_mov_b64 s[20:21], -1
	s_and_b64 vcc, exec, s[0:1]
	s_waitcnt vmcnt(31)
	v_lshlrev_b32_e32 v60, 16, v206
	v_and_b32_e32 v61, 0xffff0000, v206
	v_lshlrev_b32_e32 v206, 16, v207
	v_and_b32_e32 v207, 0xffff0000, v207
	v_pk_add_f32 v[38:39], v[38:39], v[60:61]
	v_pk_add_f32 v[40:41], v[40:41], v[206:207]
	s_cbranch_vccnz .LBB0_766
	s_mov_b64 s[20:21], 0
	global_store_dwordx4 v[52:53], v[38:41], off offset:128

; DI unsigned pk2(float a, float b) { f32x2 v = {a, b}; return __builtin_bit_cast(unsigned, __builtin_convertvector(v, bf16x2_t)); }
;   DI void finish(f32x4 (&acc)[2][2][4][2], int tb, int q, int lane) {
;     ...
;             const int c = q * 64 + 32 * b + 16 * n + 4 * fq;
;             f32x4 xo4;
;             if (f32in) xo4 = *(const f32x4*)(xs + c);
;             else {
;               const u32x2 w = *(const u32x2*)(xb_in + (size_t)tok * 1024 + c);
;               xo4[0] = __uint_as_float(w.x << 16); xo4[1] = __uint_as_float(w.x & 0xffff0000u);
;               xo4[2] = __uint_as_float(w.y << 16); xo4[3] = __uint_as_float(w.y & 0xffff0000u);
;             }
;             f32x4 v = acc[ai][b][m][n];
;             if (GRP) v = v * rc;
;             f32x4 nv;
; #pragma unroll
;             for (int j = 0; j < 4; ++j) { nv[j] = xo4[j] + v[j]; ss += nv[j] * nv[j]; }
;             if (f32out) *(f32x4*)(xout + (size_t)tok * 1024 + c) = nv;
;             else { u32x2 w; w.x = pk2(nv[0], nv[1]); w.y = pk2(nv[2], nv[3]); *(u32x2*)(xb + (size_t)tok * 1024 + c) = w; }
.LBB0_768:
	s_mov_b64 s[20:21], -1
	s_and_b64 vcc, exec, s[0:1]
	s_waitcnt vmcnt(31)
	v_lshlrev_b32_e32 v58, 16, v208
	v_and_b32_e32 v59, 0xffff0000, v208
	v_lshlrev_b32_e32 v208, 16, v209
	v_and_b32_e32 v209, 0xffff0000, v209
	v_pk_add_f32 v[34:35], v[34:35], v[58:59]
	v_pk_add_f32 v[36:37], v[36:37], v[208:209]
	s_cbranch_vccnz .LBB0_770
	s_mov_b64 s[20:21], 0
	global_store_dwordx4 v[52:53], v[34:37], off offset:192

; DI unsigned pk2(float a, float b) { f32x2 v = {a, b}; return __builtin_bit_cast(unsigned, __builtin_convertvector(v, bf16x2_t)); }
;   DI void finish(f32x4 (&acc)[2][2][4][2], int tb, int q, int lane) {
;     ...
;         const int tok = tb + ai * 128 + m * 16 + fr;
;         float rc = 1.f;
;         if (GRP) rc = tab[512 + ((tb & 255) + ai * 128 + m * 16 + fr)];
;         float ss = 0.f;
;         const bool f32in = xin0 != nullptr, f32out = xout != nullptr;
;         const float* xs = (tok < NP_TOK) ? xin0 + (size_t)tok * 1024 : xin1 + (size_t)(tok - NP_TOK) * 1024;
; #pragma unroll
;         for (int b = 0; b < 2; ++b)
; #pragma unroll
;           for (int n = 0; n < 2; ++n) {
;             const int c = q * 64 + 32 * b + 16 * n + 4 * fq;
;             f32x4 xo4;
;             if (f32in) xo4 = *(const f32x4*)(xs + c);
;             else {
;               const u32x2 w = *(const u32x2*)(xb_in + (size_t)tok * 1024 + c);
;               xo4[0] = __uint_as_float(w.x << 16); xo4[1] = __uint_as_float(w.x & 0xffff0000u);
;               xo4[2] = __uint_as_float(w.y << 16); xo4[3] = __uint_as_float(w.y & 0xffff0000u);
;             }
;             f32x4 v = acc[ai][b][m][n];
;             if (GRP) v = v * rc;
;             f32x4 nv;
; #pragma unroll
;             for (int j = 0; j < 4; ++j) { nv[j] = xo4[j] + v[j]; ss += nv[j] * nv[j]; }
;             if (f32out) *(f32x4*)(xout + (size_t)tok * 1024 + c) = nv;
;             else { u32x2 w; w.x = pk2(nv[0], nv[1]); w.y = pk2(nv[2], nv[3]); *(u32x2*)(xb + (size_t)tok * 1024 + c) = w; }
.LBB0_774:
	s_or_b64 exec, exec, s[20:21]
	v_add_u32_e32 v34, 0xa0, v132
	s_mov_b32 s20, 0x8000
	v_cmp_gt_i32_e32 vcc, s20, v34
	s_waitcnt lgkmcnt(0)
	v_ashrrev_i32_e32 v35, 31, v34
	v_readlane_b32 s20, v250, 52
	v_cndmask_b32_e32 v35, 0, v35, vcc
	v_lshlrev_b64 v[38:39], 11, v[34:35]
	v_readlane_b32 s21, v250, 53
	v_lshlrev_b64 v[36:37], 12, v[34:35]
	v_lshl_add_u64 v[36:37], s[88:89], 0, v[36:37]
	v_lshl_add_u64 v[40:41], s[20:21], 0, v[38:39]
	v_lshl_add_u64 v[40:41], v[130:131], 1, v[40:41]
	s_mov_b64 s[20:21], -1
	s_and_b64 vcc, exec, s[0:1]
	v_lshl_add_u64 v[36:37], v[130:131], 2, v[36:37]
	s_waitcnt vmcnt(31)
	v_lshlrev_b32_e32 v44, 16, v210
	v_and_b32_e32 v45, 0xffff0000, v210
	v_lshlrev_b32_e32 v210, 16, v211
	v_and_b32_e32 v211, 0xffff0000, v211
	v_pk_add_f32 v[30:31], v[30:31], v[44:45]
	v_pk_add_f32 v[32:33], v[32:33], v[210:211]
	s_cbranch_vccnz .LBB0_776
	s_mov_b64 s[20:21], 0
	global_store_dwordx4 v[36:37], v[30:33], off

; DI unsigned pk2(float a, float b) { f32x2 v = {a, b}; return __builtin_bit_cast(unsigned, __builtin_convertvector(v, bf16x2_t)); }
;   DI void finish(f32x4 (&acc)[2][2][4][2], int tb, int q, int lane) {
;     ...
;             const int c = q * 64 + 32 * b + 16 * n + 4 * fq;
;             f32x4 xo4;
;             if (f32in) xo4 = *(const f32x4*)(xs + c);
;             else {
;               const u32x2 w = *(const u32x2*)(xb_in + (size_t)tok * 1024 + c);
;               xo4[0] = __uint_as_float(w.x << 16); xo4[1] = __uint_as_float(w.x & 0xffff0000u);
;               xo4[2] = __uint_as_float(w.y << 16); xo4[3] = __uint_as_float(w.y & 0xffff0000u);
;             }
;             f32x4 v = acc[ai][b][m][n];
;             if (GRP) v = v * rc;
;             f32x4 nv;
; #pragma unroll
;             for (int j = 0; j < 4; ++j) { nv[j] = xo4[j] + v[j]; ss += nv[j] * nv[j]; }
;             if (f32out) *(f32x4*)(xout + (size_t)tok * 1024 + c) = nv;
;             else { u32x2 w; w.x = pk2(nv[0], nv[1]); w.y = pk2(nv[2], nv[3]); *(u32x2*)(xb + (size_t)tok * 1024 + c) = w; }
.LBB0_778:
	s_mov_b64 s[20:21], -1
	s_and_b64 vcc, exec, s[0:1]
	s_waitcnt vmcnt(31)
	v_lshlrev_b32_e32 v44, 16, v214
	v_and_b32_e32 v45, 0xffff0000, v214
	v_lshlrev_b32_e32 v214, 16, v215
	v_and_b32_e32 v215, 0xffff0000, v215
	v_pk_add_f32 v[26:27], v[26:27], v[44:45]
	v_pk_add_f32 v[28:29], v[28:29], v[214:215]
	s_cbranch_vccnz .LBB0_780
	s_mov_b64 s[20:21], 0
	global_store_dwordx4 v[36:37], v[26:29], off offset:64

; DI unsigned pk2(float a, float b) { f32x2 v = {a, b}; return __builtin_bit_cast(unsigned, __builtin_convertvector(v, bf16x2_t)); }
;   DI void finish(f32x4 (&acc)[2][2][4][2], int tb, int q, int lane) {
;     ...
;             const int c = q * 64 + 32 * b + 16 * n + 4 * fq;
;             f32x4 xo4;
;             if (f32in) xo4 = *(const f32x4*)(xs + c);
;             else {
;               const u32x2 w = *(const u32x2*)(xb_in + (size_t)tok * 1024 + c);
;               xo4[0] = __uint_as_float(w.x << 16); xo4[1] = __uint_as_float(w.x & 0xffff0000u);
;               xo4[2] = __uint_as_float(w.y << 16); xo4[3] = __uint_as_float(w.y & 0xffff0000u);
;             }
;             f32x4 v = acc[ai][b][m][n];
;             if (GRP) v = v * rc;
;             f32x4 nv;
; #pragma unroll
;             for (int j = 0; j < 4; ++j) { nv[j] = xo4[j] + v[j]; ss += nv[j] * nv[j]; }
;             if (f32out) *(f32x4*)(xout + (size_t)tok * 1024 + c) = nv;
;             else { u32x2 w; w.x = pk2(nv[0], nv[1]); w.y = pk2(nv[2], nv[3]); *(u32x2*)(xb + (size_t)tok * 1024 + c) = w; }
.LBB0_782:
	s_mov_b64 s[20:21], -1
	s_and_b64 vcc, exec, s[0:1]
	s_waitcnt vmcnt(31)
	v_lshlrev_b32_e32 v44, 16, v216
	v_and_b32_e32 v45, 0xffff0000, v216
	v_lshlrev_b32_e32 v216, 16, v217
	v_and_b32_e32 v217, 0xffff0000, v217
	v_pk_add_f32 v[22:23], v[22:23], v[44:45]
	v_pk_add_f32 v[24:25], v[24:25], v[216:217]
	s_cbranch_vccnz .LBB0_784
	s_mov_b64 s[20:21], 0
	global_store_dwordx4 v[36:37], v[22:25], off offset:128

; DI unsigned pk2(float a, float b) { f32x2 v = {a, b}; return __builtin_bit_cast(unsigned, __builtin_convertvector(v, bf16x2_t)); }
;   DI void finish(f32x4 (&acc)[2][2][4][2], int tb, int q, int lane) {
;     ...
;             const int c = q * 64 + 32 * b + 16 * n + 4 * fq;
;             f32x4 xo4;
;             if (f32in) xo4 = *(const f32x4*)(xs + c);
;             else {
;               const u32x2 w = *(const u32x2*)(xb_in + (size_t)tok * 1024 + c);
;               xo4[0] = __uint_as_float(w.x << 16); xo4[1] = __uint_as_float(w.x & 0xffff0000u);
;               xo4[2] = __uint_as_float(w.y << 16); xo4[3] = __uint_as_float(w.y & 0xffff0000u);
;             }
;             f32x4 v = acc[ai][b][m][n];
;             if (GRP) v = v * rc;
;             f32x4 nv;
; #pragma unroll
;             for (int j = 0; j < 4; ++j) { nv[j] = xo4[j] + v[j]; ss += nv[j] * nv[j]; }
;             if (f32out) *(f32x4*)(xout + (size_t)tok * 1024 + c) = nv;
;             else { u32x2 w; w.x = pk2(nv[0], nv[1]); w.y = pk2(nv[2], nv[3]); *(u32x2*)(xb + (size_t)tok * 1024 + c) = w; }
.LBB0_786:
	s_mov_b64 s[20:21], -1
	s_and_b64 vcc, exec, s[0:1]
	s_waitcnt vmcnt(31)
	v_lshlrev_b32_e32 v42, 16, v218
	v_and_b32_e32 v43, 0xffff0000, v218
	v_lshlrev_b32_e32 v218, 16, v219
	v_and_b32_e32 v219, 0xffff0000, v219
	v_pk_add_f32 v[18:19], v[18:19], v[42:43]
	v_pk_add_f32 v[20:21], v[20:21], v[218:219]
	s_cbranch_vccnz .LBB0_788
	s_mov_b64 s[20:21], 0
	global_store_dwordx4 v[36:37], v[18:21], off offset:192

; DI unsigned pk2(float a, float b) { f32x2 v = {a, b}; return __builtin_bit_cast(unsigned, __builtin_convertvector(v, bf16x2_t)); }
;   DI void finish(f32x4 (&acc)[2][2][4][2], int tb, int q, int lane) {
;     ...
;         const int tok = tb + ai * 128 + m * 16 + fr;
;         float rc = 1.f;
;         if (GRP) rc = tab[512 + ((tb & 255) + ai * 128 + m * 16 + fr)];
;         float ss = 0.f;
;         const bool f32in = xin0 != nullptr, f32out = xout != nullptr;
;         const float* xs = (tok < NP_TOK) ? xin0 + (size_t)tok * 1024 : xin1 + (size_t)(tok - NP_TOK) * 1024;
; #pragma unroll
;         for (int b = 0; b < 2; ++b)
; #pragma unroll
;           for (int n = 0; n < 2; ++n) {
;             const int c = q * 64 + 32 * b + 16 * n + 4 * fq;
;             f32x4 xo4;
;             if (f32in) xo4 = *(const f32x4*)(xs + c);
;             else {
;               const u32x2 w = *(const u32x2*)(xb_in + (size_t)tok * 1024 + c);
;               xo4[0] = __uint_as_float(w.x << 16); xo4[1] = __uint_as_float(w.x & 0xffff0000u);
;               xo4[2] = __uint_as_float(w.y << 16); xo4[3] = __uint_as_float(w.y & 0xffff0000u);
;             }
;             f32x4 v = acc[ai][b][m][n];
;             if (GRP) v = v * rc;
;             f32x4 nv;
; #pragma unroll
;             for (int j = 0; j < 4; ++j) { nv[j] = xo4[j] + v[j]; ss += nv[j] * nv[j]; }
;             if (f32out) *(f32x4*)(xout + (size_t)tok * 1024 + c) = nv;
;             else { u32x2 w; w.x = pk2(nv[0], nv[1]); w.y = pk2(nv[2], nv[3]); *(u32x2*)(xb + (size_t)tok * 1024 + c) = w; }
.LBB0_792:
	s_or_b64 exec, exec, s[20:21]
	v_add_u32_e32 v18, 0xb0, v132
	s_mov_b32 s20, 0x8000
	v_cmp_gt_i32_e32 vcc, s20, v18
	s_waitcnt lgkmcnt(0)
	v_ashrrev_i32_e32 v19, 31, v18
	v_readlane_b32 s20, v250, 52
	v_cndmask_b32_e32 v19, 0, v19, vcc
	v_lshlrev_b64 v[24:25], 11, v[18:19]
	v_readlane_b32 s21, v250, 53
	v_lshlrev_b64 v[22:23], 12, v[18:19]
	v_lshl_add_u64 v[22:23], s[88:89], 0, v[22:23]
	v_lshl_add_u64 v[20:21], s[20:21], 0, v[24:25]
	v_lshl_add_u64 v[20:21], v[130:131], 1, v[20:21]
	s_mov_b64 s[20:21], -1
	s_and_b64 vcc, exec, s[0:1]
	v_lshl_add_u64 v[22:23], v[130:131], 2, v[22:23]
	s_waitcnt vmcnt(31)
	v_lshlrev_b32_e32 v28, 16, v220
	v_and_b32_e32 v29, 0xffff0000, v220
	v_lshlrev_b32_e32 v220, 16, v221
	v_and_b32_e32 v221, 0xffff0000, v221
	v_pk_add_f32 v[14:15], v[14:15], v[28:29]
	v_pk_add_f32 v[16:17], v[16:17], v[220:221]
	s_cbranch_vccnz .LBB0_794
	s_mov_b64 s[20:21], 0
	global_store_dwordx4 v[22:23], v[14:17], off

; DI unsigned pk2(float a, float b) { f32x2 v = {a, b}; return __builtin_bit_cast(unsigned, __builtin_convertvector(v, bf16x2_t)); }
;   DI void finish(f32x4 (&acc)[2][2][4][2], int tb, int q, int lane) {
;     ...
;             const int c = q * 64 + 32 * b + 16 * n + 4 * fq;
;             f32x4 xo4;
;             if (f32in) xo4 = *(const f32x4*)(xs + c);
;             else {
;               const u32x2 w = *(const u32x2*)(xb_in + (size_t)tok * 1024 + c);
;               xo4[0] = __uint_as_float(w.x << 16); xo4[1] = __uint_as_float(w.x & 0xffff0000u);
;               xo4[2] = __uint_as_float(w.y << 16); xo4[3] = __uint_as_float(w.y & 0xffff0000u);
;             }
;             f32x4 v = acc[ai][b][m][n];
;             if (GRP) v = v * rc;
;             f32x4 nv;
; #pragma unroll
;             for (int j = 0; j < 4; ++j) { nv[j] = xo4[j] + v[j]; ss += nv[j] * nv[j]; }
;             if (f32out) *(f32x4*)(xout + (size_t)tok * 1024 + c) = nv;
;             else { u32x2 w; w.x = pk2(nv[0], nv[1]); w.y = pk2(nv[2], nv[3]); *(u32x2*)(xb + (size_t)tok * 1024 + c) = w; }
.LBB0_796:
	s_mov_b64 s[20:21], -1
	s_and_b64 vcc, exec, s[0:1]
	s_waitcnt vmcnt(31)
	v_lshlrev_b32_e32 v28, 16, v222
	v_and_b32_e32 v29, 0xffff0000, v222
	v_lshlrev_b32_e32 v222, 16, v223
	v_and_b32_e32 v223, 0xffff0000, v223
	v_pk_add_f32 v[10:11], v[10:11], v[28:29]
	v_pk_add_f32 v[12:13], v[12:13], v[222:223]
	s_cbranch_vccnz .LBB0_798
	s_mov_b64 s[20:21], 0
	global_store_dwordx4 v[22:23], v[10:13], off offset:64

; DI unsigned pk2(float a, float b) { f32x2 v = {a, b}; return __builtin_bit_cast(unsigned, __builtin_convertvector(v, bf16x2_t)); }
;   DI void finish(f32x4 (&acc)[2][2][4][2], int tb, int q, int lane) {
;     ...
;             const int c = q * 64 + 32 * b + 16 * n + 4 * fq;
;             f32x4 xo4;
;             if (f32in) xo4 = *(const f32x4*)(xs + c);
;             else {
;               const u32x2 w = *(const u32x2*)(xb_in + (size_t)tok * 1024 + c);
;               xo4[0] = __uint_as_float(w.x << 16); xo4[1] = __uint_as_float(w.x & 0xffff0000u);
;               xo4[2] = __uint_as_float(w.y << 16); xo4[3] = __uint_as_float(w.y & 0xffff0000u);
;             }
;             f32x4 v = acc[ai][b][m][n];
;             if (GRP) v = v * rc;
;             f32x4 nv;
; #pragma unroll
;             for (int j = 0; j < 4; ++j) { nv[j] = xo4[j] + v[j]; ss += nv[j] * nv[j]; }
;             if (f32out) *(f32x4*)(xout + (size_t)tok * 1024 + c) = nv;
;             else { u32x2 w; w.x = pk2(nv[0], nv[1]); w.y = pk2(nv[2], nv[3]); *(u32x2*)(xb + (size_t)tok * 1024 + c) = w; }
.LBB0_800:
	s_mov_b64 s[20:21], -1
	s_and_b64 vcc, exec, s[0:1]
	s_waitcnt vmcnt(31)
	v_lshlrev_b32_e32 v28, 16, v224
	v_and_b32_e32 v29, 0xffff0000, v224
	v_lshlrev_b32_e32 v224, 16, v225
	v_and_b32_e32 v225, 0xffff0000, v225
	v_pk_add_f32 v[6:7], v[6:7], v[28:29]
	v_pk_add_f32 v[8:9], v[8:9], v[224:225]
	s_cbranch_vccnz .LBB0_802
	s_mov_b64 s[20:21], 0
	global_store_dwordx4 v[22:23], v[6:9], off offset:128

; DI unsigned pk2(float a, float b) { f32x2 v = {a, b}; return __builtin_bit_cast(unsigned, __builtin_convertvector(v, bf16x2_t)); }
;   DI void finish(f32x4 (&acc)[2][2][4][2], int tb, int q, int lane) {
;     ...
;             const int c = q * 64 + 32 * b + 16 * n + 4 * fq;
;             f32x4 xo4;
;             if (f32in) xo4 = *(const f32x4*)(xs + c);
;             else {
;               const u32x2 w = *(const u32x2*)(xb_in + (size_t)tok * 1024 + c);
;               xo4[0] = __uint_as_float(w.x << 16); xo4[1] = __uint_as_float(w.x & 0xffff0000u);
;               xo4[2] = __uint_as_float(w.y << 16); xo4[3] = __uint_as_float(w.y & 0xffff0000u);
;             }
;             f32x4 v = acc[ai][b][m][n];
;             if (GRP) v = v * rc;
;             f32x4 nv;
; #pragma unroll
;             for (int j = 0; j < 4; ++j) { nv[j] = xo4[j] + v[j]; ss += nv[j] * nv[j]; }
;             if (f32out) *(f32x4*)(xout + (size_t)tok * 1024 + c) = nv;
;             else { u32x2 w; w.x = pk2(nv[0], nv[1]); w.y = pk2(nv[2], nv[3]); *(u32x2*)(xb + (size_t)tok * 1024 + c) = w; }
.LBB0_804:
	s_and_b64 vcc, exec, s[0:1]
	s_mov_b64 s[0:1], -1
	s_waitcnt vmcnt(31)
	v_lshlrev_b32_e32 v26, 16, v226
	v_and_b32_e32 v27, 0xffff0000, v226
	v_lshlrev_b32_e32 v226, 16, v227
	v_and_b32_e32 v227, 0xffff0000, v227
	v_pk_add_f32 v[2:3], v[2:3], v[26:27]
	v_pk_add_f32 v[4:5], v[4:5], v[226:227]
	s_cbranch_vccnz .LBB0_806
	s_mov_b64 s[0:1], 0
	global_store_dwordx4 v[22:23], v[2:5], off offset:192
